# P2: batched gate/gain loads in finalizes (global instead of flat), balanced tile assignment (diff 15-j & 7-j, retention pair 2j+1,2j)
# speedup vs baseline: 1.0134x; 1.0134x over previous
; template <bool DIFF>
; __device__ __forceinline__ void attn_item(LAS unsigned char* lds, const bf16_t* Z, bf16_t* MIX, int b, int h, int t, float lam, float shift, const float* gain, int tid, int wid, int lane) {
;     ...
;     float inv0 = 1.f, inv1 = 0.f;
;     if (DIFF) {
; #pragma unroll
;         for (int c = 0; c < NC; ++c) l[c] = quad_sum(l[c]);
;         inv0 = 1.0f / l[0]; inv1 = lam / l[NC - 1];
;     }
;     float ss = 0.f;
; #pragma unroll
;     for (int eb = 0; eb < 8; ++eb)
; #pragma unroll
;         for (int i = 0; i < 4; ++i) { float v = O[0][eb][i] * inv0; if (DIFF) v -= O[NC - 1][eb][i] * inv1; O[0][eb][i] = v; ss += v * v; }
;     ss = quad_sum(ss);
;     const float r = rsqrtf(ss * (1.0f / 128.0f) + EPS) * (DIFF ? 0.8f : 1.0f);
;     const int row = row0 + q16;
;     const bf16_t* gp = Z + (size_t)row * DIN + gcol + 4 * quad;
;     bf16_t* op = MIX + (size_t)row * DM + (DIFF ? 1024 : 0) + 128 * h + 4 * quad;
; #pragma unroll
;     for (int eb = 0; eb < 8; ++eb) {
;         const u32x2 gw = *(const u32x2*)(gp + 16 * eb);
;         const f32x4 gn = *(const f32x4*)(gain + 16 * eb + 4 * quad);
.LBB0_564:
	s_waitcnt lgkmcnt(0)
	ds_swizzle_b32 v68, v133 offset:swizzle(SWAP,16)
	ds_swizzle_b32 v69, v132 offset:swizzle(SWAP,16)
	v_ashrrev_i32_e32 v129, 31, v128
	v_lshlrev_b64 v[80:81], 1, v[128:129]
	s_mov_b32 s87, s27
	s_waitcnt lgkmcnt(0)
	v_add_f32_e32 v68, v133, v68
	v_mov_b32_e32 v70, v68
	s_nop 1
	v_permlane32_swap_b32_e32 v68, v70
	v_add_f32_e32 v68, v68, v70
	v_div_scale_f32 v70, s[0:1], v68, v68, 1.0
	v_rcp_f32_e32 v72, v70
	v_add_f32_e32 v69, v132, v69
	v_mov_b32_e32 v71, v69
	s_nop 1
	v_permlane32_swap_b32_e32 v69, v71
	v_add_f32_e32 v69, v69, v71
	v_fma_f32 v71, -v70, v72, 1.0
	v_fmac_f32_e32 v72, v71, v72
	v_div_scale_f32 v71, vcc, 1.0, v68, 1.0
	v_mul_f32_e32 v73, v71, v72
	v_fma_f32 v74, -v70, v73, v71
	v_fmac_f32_e32 v73, v74, v72
	v_fma_f32 v70, -v70, v73, v71
	v_div_scale_f32 v71, s[0:1], v69, v69, s28
	v_rcp_f32_e32 v74, v71
	v_div_fmas_f32 v70, v70, v72, v73
	v_div_fixup_f32 v76, v70, v68, 1.0
	s_movk_i32 s0, 0x3000
	v_fma_f32 v68, -v71, v74, 1.0
	v_fmac_f32_e32 v74, v68, v74
	v_div_scale_f32 v68, vcc, s28, v69, s28
	v_mul_f32_e32 v70, v68, v74
	v_fma_f32 v72, -v71, v70, v68
	v_fmac_f32_e32 v70, v72, v74
	v_fma_f32 v68, -v71, v70, v68
	v_lshl_add_u64 v[72:73], v[126:127], 0, v[80:81]
	v_div_fmas_f32 v68, v68, v74, v70
	v_lshl_add_u64 v[70:71], v[72:73], 0, s[92:93]
	v_add_co_u32_e32 v72, vcc, s0, v72
	v_div_fixup_f32 v78, v68, v69, s28
	v_lshlrev_b64 v[68:69], 12, v[124:125]
	v_addc_co_u32_e32 v73, vcc, 0, v73, vcc
	v_lshl_add_u64 v[82:83], s[88:89], 0, v[68:69]
	v_lshl_add_u64 v[68:69], v[128:129], 2, s[84:85]
	global_load_dwordx2 v[116:117], v[70:71], off
	global_load_dwordx4 v[84:87], v[68:69], off
	global_load_dwordx2 v[118:119], v[70:71], off offset:32
	global_load_dwordx4 v[88:91], v[68:69], off offset:64
	global_load_dwordx2 v[120:121], v[70:71], off offset:64
	global_load_dwordx4 v[92:95], v[68:69], off offset:128
	global_load_dwordx2 v[122:123], v[70:71], off offset:96
	global_load_dwordx4 v[96:99], v[68:69], off offset:192
	global_load_dwordx2 v[132:133], v[70:71], off offset:128
	global_load_dwordx4 v[100:103], v[68:69], off offset:256
	global_load_dwordx2 v[134:135], v[70:71], off offset:160
	global_load_dwordx4 v[104:107], v[68:69], off offset:320
	global_load_dwordx2 v[136:137], v[70:71], off offset:192
	global_load_dwordx4 v[108:111], v[68:69], off offset:384
	global_load_dwordx2 v[138:139], v[70:71], off offset:224
	global_load_dwordx4 v[112:115], v[68:69], off offset:448
	v_pk_mul_f32 v[60:61], v[60:61], v[78:79] op_sel_hi:[1,0]
	v_pk_mul_f32 v[62:63], v[62:63], v[78:79] op_sel_hi:[1,0]
	v_pk_fma_f32 v[60:61], v[64:65], v[76:77], v[60:61] op_sel_hi:[1,0,1] neg_lo:[0,0,1] neg_hi:[0,0,1]
	v_pk_fma_f32 v[62:63], v[66:67], v[76:77], v[62:63] op_sel_hi:[1,0,1] neg_lo:[0,0,1] neg_hi:[0,0,1]
	v_pk_mul_f32 v[64:65], v[60:61], v[60:61]
	v_pk_mul_f32 v[66:67], v[62:63], v[62:63]
	v_pk_mul_f32 v[52:53], v[52:53], v[78:79] op_sel_hi:[1,0]
	v_add_f32_e32 v64, v64, v65
	v_pk_fma_f32 v[52:53], v[56:57], v[76:77], v[52:53] op_sel_hi:[1,0,1] neg_lo:[0,0,1] neg_hi:[0,0,1]
	v_add_f32_e32 v64, v66, v64
	v_pk_mul_f32 v[54:55], v[54:55], v[78:79] op_sel_hi:[1,0]
	v_pk_mul_f32 v[56:57], v[52:53], v[52:53]
	v_add_f32_e32 v64, v67, v64
	v_pk_fma_f32 v[54:55], v[58:59], v[76:77], v[54:55] op_sel_hi:[1,0,1] neg_lo:[0,0,1] neg_hi:[0,0,1]
	v_add_f32_e32 v56, v56, v64
	v_pk_mul_f32 v[58:59], v[54:55], v[54:55]
	v_pk_mul_f32 v[44:45], v[44:45], v[78:79] op_sel_hi:[1,0]
	v_add_f32_e32 v56, v57, v56
	v_pk_fma_f32 v[44:45], v[48:49], v[76:77], v[44:45] op_sel_hi:[1,0,1] neg_lo:[0,0,1] neg_hi:[0,0,1]
	v_add_f32_e32 v56, v58, v56
	v_pk_mul_f32 v[46:47], v[46:47], v[78:79] op_sel_hi:[1,0]
	v_pk_mul_f32 v[48:49], v[44:45], v[44:45]
	v_add_f32_e32 v56, v59, v56
	v_pk_fma_f32 v[46:47], v[50:51], v[76:77], v[46:47] op_sel_hi:[1,0,1] neg_lo:[0,0,1] neg_hi:[0,0,1]
	v_add_f32_e32 v48, v48, v56
	v_pk_mul_f32 v[50:51], v[46:47], v[46:47]
	v_pk_mul_f32 v[36:37], v[36:37], v[78:79] op_sel_hi:[1,0]
	v_add_f32_e32 v48, v49, v48
	v_pk_fma_f32 v[36:37], v[40:41], v[76:77], v[36:37] op_sel_hi:[1,0,1] neg_lo:[0,0,1] neg_hi:[0,0,1]
	v_add_f32_e32 v48, v50, v48
	v_pk_mul_f32 v[38:39], v[38:39], v[78:79] op_sel_hi:[1,0]
	v_pk_mul_f32 v[40:41], v[36:37], v[36:37]
	v_add_f32_e32 v48, v51, v48
	v_pk_fma_f32 v[38:39], v[42:43], v[76:77], v[38:39] op_sel_hi:[1,0,1] neg_lo:[0,0,1] neg_hi:[0,0,1]
	v_add_f32_e32 v40, v40, v48
	v_pk_mul_f32 v[42:43], v[38:39], v[38:39]
	v_pk_mul_f32 v[28:29], v[28:29], v[78:79] op_sel_hi:[1,0]
	v_add_f32_e32 v40, v41, v40
	v_pk_fma_f32 v[28:29], v[32:33], v[76:77], v[28:29] op_sel_hi:[1,0,1] neg_lo:[0,0,1] neg_hi:[0,0,1]
	v_add_f32_e32 v40, v42, v40
	v_pk_mul_f32 v[30:31], v[30:31], v[78:79] op_sel_hi:[1,0]
	v_pk_mul_f32 v[32:33], v[28:29], v[28:29]
	v_add_f32_e32 v40, v43, v40
	v_pk_fma_f32 v[30:31], v[34:35], v[76:77], v[30:31] op_sel_hi:[1,0,1] neg_lo:[0,0,1] neg_hi:[0,0,1]
	v_add_f32_e32 v32, v32, v40
	v_pk_mul_f32 v[34:35], v[30:31], v[30:31]
	v_pk_mul_f32 v[20:21], v[20:21], v[78:79] op_sel_hi:[1,0]
	v_add_f32_e32 v32, v33, v32
	v_pk_fma_f32 v[20:21], v[24:25], v[76:77], v[20:21] op_sel_hi:[1,0,1] neg_lo:[0,0,1] neg_hi:[0,0,1]
	v_add_f32_e32 v32, v34, v32
	v_pk_mul_f32 v[22:23], v[22:23], v[78:79] op_sel_hi:[1,0]
	v_pk_mul_f32 v[24:25], v[20:21], v[20:21]
	v_add_f32_e32 v32, v35, v32
	v_pk_fma_f32 v[22:23], v[26:27], v[76:77], v[22:23] op_sel_hi:[1,0,1] neg_lo:[0,0,1] neg_hi:[0,0,1]
	v_add_f32_e32 v24, v24, v32
	v_pk_mul_f32 v[26:27], v[22:23], v[22:23]
	v_pk_mul_f32 v[12:13], v[12:13], v[78:79] op_sel_hi:[1,0]
	v_add_f32_e32 v24, v25, v24
	v_pk_fma_f32 v[12:13], v[16:17], v[76:77], v[12:13] op_sel_hi:[1,0,1] neg_lo:[0,0,1] neg_hi:[0,0,1]
	v_add_f32_e32 v24, v26, v24
	v_pk_mul_f32 v[14:15], v[14:15], v[78:79] op_sel_hi:[1,0]
	v_pk_mul_f32 v[16:17], v[12:13], v[12:13]
	v_add_f32_e32 v24, v27, v24
	v_pk_fma_f32 v[14:15], v[18:19], v[76:77], v[14:15] op_sel_hi:[1,0,1] neg_lo:[0,0,1] neg_hi:[0,0,1]
	v_add_f32_e32 v16, v16, v24
	v_pk_mul_f32 v[18:19], v[14:15], v[14:15]
	v_pk_mul_f32 v[4:5], v[4:5], v[78:79] op_sel_hi:[1,0]
	v_add_f32_e32 v16, v17, v16
	v_pk_fma_f32 v[8:9], v[8:9], v[76:77], v[4:5] op_sel_hi:[1,0,1] neg_lo:[0,0,1] neg_hi:[0,0,1]
	v_add_f32_e32 v16, v18, v16
	v_pk_mul_f32 v[6:7], v[6:7], v[78:79] op_sel_hi:[1,0]
	v_pk_mul_f32 v[4:5], v[8:9], v[8:9]
	v_add_f32_e32 v16, v19, v16
	v_pk_fma_f32 v[10:11], v[10:11], v[76:77], v[6:7] op_sel_hi:[1,0,1] neg_lo:[0,0,1] neg_hi:[0,0,1]
	v_add_f32_e32 v4, v4, v16
	v_pk_mul_f32 v[6:7], v[10:11], v[10:11]
	v_add_f32_e32 v4, v5, v4
	v_add_f32_e32 v4, v6, v4
	v_add_f32_e32 v6, v7, v4
	ds_swizzle_b32 v7, v6 offset:swizzle(SWAP,16)
	v_mov_b32_e32 v18, 0x358637bd
	v_lshl_add_u64 v[4:5], v[82:83], 0, s[86:87]
	v_lshl_add_u64 v[16:17], v[4:5], 0, v[80:81]
	s_waitcnt lgkmcnt(0)
; __device__ __forceinline__ unsigned cvtpk(float lo, float hi) { f32x2 v = {lo, hi}; bf16x2_t b = __builtin_convertvector(v, bf16x2_t); return __builtin_bit_cast(unsigned, b); }
; __device__ __forceinline__ float bflo(unsigned u) { return __uint_as_float(u << 16); }
; __device__ __forceinline__ float bfhi(unsigned u) { return __uint_as_float(u & 0xffff0000u); }
; template <bool DIFF>
; __device__ __forceinline__ void attn_item(LAS unsigned char* lds, const bf16_t* Z, bf16_t* MIX, int b, int h, int t, float lam, float shift, const float* gain, int tid, int wid, int lane) {
;     ...
;     const float r = rsqrtf(ss * (1.0f / 128.0f) + EPS) * (DIFF ? 0.8f : 1.0f);
;     const int row = row0 + q16;
;     const bf16_t* gp = Z + (size_t)row * DIN + gcol + 4 * quad;
;     bf16_t* op = MIX + (size_t)row * DM + (DIFF ? 1024 : 0) + 128 * h + 4 * quad;
; #pragma unroll
;     for (int eb = 0; eb < 8; ++eb) {
;         const u32x2 gw = *(const u32x2*)(gp + 16 * eb);
;         const f32x4 gn = *(const f32x4*)(gain + 16 * eb + 4 * quad);
;         u32x2 w; w.x = cvtpk(O[0][eb][0] * r * gn.x * bflo(gw.x), O[0][eb][1] * r * gn.y * bfhi(gw.x));
;         w.y = cvtpk(O[0][eb][2] * r * gn.z * bflo(gw.y), O[0][eb][3] * r * gn.w * bfhi(gw.y));
;         *(u32x2*)(op + 16 * eb) = w;
;     }
; __global__ void __launch_bounds__(NWAVES * 64, 2) fwd(Args args) {
;     ...
;         for (int pi = vcu; pi < 256; pi += G) {
;             const int bh = pi >> 3, tp = pi & 7, b = bh >> 3, h = bh & 7;
	v_add_f32_e32 v6, v6, v7
	v_mov_b32_e32 v7, v6
	s_nop 1
	v_permlane32_swap_b32_e32 v6, v7
	v_add_f32_e32 v6, v6, v7
	v_fmamk_f32 v6, v6, 0x3c000000, v18
	v_mul_f32_e32 v7, 0x4b800000, v6
	v_cmp_gt_f32_e32 vcc, s42, v6
	s_nop 1
	v_cndmask_b32_e32 v6, v6, v7, vcc
	v_rsq_f32_e32 v24, v6
	s_nop 0
	v_mul_f32_e32 v25, 0x45800000, v24
	v_cndmask_b32_e32 v24, v24, v25, vcc
	v_mul_f32_e32 v24, 0x3f4ccccd, v24
	s_waitcnt vmcnt(0)
	v_pk_mul_f32 v[60:61], v[60:61], v[24:25] op_sel_hi:[1,0]
	v_pk_mul_f32 v[62:63], v[62:63], v[24:25] op_sel_hi:[1,0]
	v_lshlrev_b32_e32 v56, 16, v116
	v_and_b32_e32 v57, 0xffff0000, v116
	v_lshlrev_b32_e32 v58, 16, v117
	v_and_b32_e32 v59, 0xffff0000, v117
	v_pk_mul_f32 v[60:61], v[84:85], v[60:61]
	v_pk_mul_f32 v[62:63], v[86:87], v[62:63]
	v_pk_mul_f32 v[60:61], v[60:61], v[56:57]
	v_pk_mul_f32 v[62:63], v[62:63], v[58:59]
	v_cvt_pk_bf16_f32 v60, v60, v61
	v_cvt_pk_bf16_f32 v61, v62, v63
	global_store_dwordx2 v[16:17], v[60:61], off offset:2048
	v_pk_mul_f32 v[52:53], v[52:53], v[24:25] op_sel_hi:[1,0]
	v_pk_mul_f32 v[54:55], v[54:55], v[24:25] op_sel_hi:[1,0]
	v_lshlrev_b32_e32 v40, 16, v118
	v_and_b32_e32 v41, 0xffff0000, v118
	v_lshlrev_b32_e32 v42, 16, v119
	v_and_b32_e32 v43, 0xffff0000, v119
	v_pk_mul_f32 v[52:53], v[88:89], v[52:53]
	v_pk_mul_f32 v[54:55], v[90:91], v[54:55]
	v_pk_mul_f32 v[52:53], v[52:53], v[40:41]
	v_pk_mul_f32 v[54:55], v[54:55], v[42:43]
	v_cvt_pk_bf16_f32 v52, v52, v53
	v_cvt_pk_bf16_f32 v53, v54, v55
	global_store_dwordx2 v[16:17], v[52:53], off offset:2080
	v_pk_mul_f32 v[44:45], v[44:45], v[24:25] op_sel_hi:[1,0]
	v_pk_mul_f32 v[46:47], v[46:47], v[24:25] op_sel_hi:[1,0]
	v_lshlrev_b32_e32 v56, 16, v120
	v_and_b32_e32 v57, 0xffff0000, v120
	v_lshlrev_b32_e32 v58, 16, v121
	v_and_b32_e32 v59, 0xffff0000, v121
	v_pk_mul_f32 v[44:45], v[92:93], v[44:45]
	v_pk_mul_f32 v[46:47], v[94:95], v[46:47]
	v_pk_mul_f32 v[44:45], v[44:45], v[56:57]
	v_pk_mul_f32 v[46:47], v[46:47], v[58:59]
	v_cvt_pk_bf16_f32 v44, v44, v45
	v_cvt_pk_bf16_f32 v45, v46, v47
	global_store_dwordx2 v[16:17], v[44:45], off offset:2112
	v_pk_mul_f32 v[36:37], v[36:37], v[24:25] op_sel_hi:[1,0]
	v_pk_mul_f32 v[38:39], v[38:39], v[24:25] op_sel_hi:[1,0]
	v_lshlrev_b32_e32 v40, 16, v122
	v_and_b32_e32 v41, 0xffff0000, v122
	v_lshlrev_b32_e32 v42, 16, v123
	v_and_b32_e32 v43, 0xffff0000, v123
	v_pk_mul_f32 v[36:37], v[96:97], v[36:37]
	v_pk_mul_f32 v[38:39], v[98:99], v[38:39]
	v_pk_mul_f32 v[36:37], v[36:37], v[40:41]
	v_pk_mul_f32 v[38:39], v[38:39], v[42:43]
	v_cvt_pk_bf16_f32 v36, v36, v37
	v_cvt_pk_bf16_f32 v37, v38, v39
	global_store_dwordx2 v[16:17], v[36:37], off offset:2144
	v_pk_mul_f32 v[28:29], v[28:29], v[24:25] op_sel_hi:[1,0]
	v_pk_mul_f32 v[30:31], v[30:31], v[24:25] op_sel_hi:[1,0]
	v_lshlrev_b32_e32 v56, 16, v132
	v_and_b32_e32 v57, 0xffff0000, v132
	v_lshlrev_b32_e32 v58, 16, v133
	v_and_b32_e32 v59, 0xffff0000, v133
	v_pk_mul_f32 v[28:29], v[100:101], v[28:29]
	v_pk_mul_f32 v[30:31], v[102:103], v[30:31]
	v_pk_mul_f32 v[28:29], v[28:29], v[56:57]
	v_pk_mul_f32 v[30:31], v[30:31], v[58:59]
	v_cvt_pk_bf16_f32 v28, v28, v29
	v_cvt_pk_bf16_f32 v29, v30, v31
	global_store_dwordx2 v[16:17], v[28:29], off offset:2176
	v_pk_mul_f32 v[20:21], v[20:21], v[24:25] op_sel_hi:[1,0]
	v_pk_mul_f32 v[22:23], v[22:23], v[24:25] op_sel_hi:[1,0]
	v_lshlrev_b32_e32 v40, 16, v134
	v_and_b32_e32 v41, 0xffff0000, v134
	v_lshlrev_b32_e32 v42, 16, v135
	v_and_b32_e32 v43, 0xffff0000, v135
	v_pk_mul_f32 v[20:21], v[104:105], v[20:21]
	v_pk_mul_f32 v[22:23], v[106:107], v[22:23]
	v_pk_mul_f32 v[20:21], v[20:21], v[40:41]
	v_pk_mul_f32 v[22:23], v[22:23], v[42:43]
	v_cvt_pk_bf16_f32 v20, v20, v21
	v_cvt_pk_bf16_f32 v21, v22, v23
	global_store_dwordx2 v[16:17], v[20:21], off offset:2208
	v_pk_mul_f32 v[12:13], v[12:13], v[24:25] op_sel_hi:[1,0]
	v_pk_mul_f32 v[14:15], v[14:15], v[24:25] op_sel_hi:[1,0]
	v_lshlrev_b32_e32 v56, 16, v136
	v_and_b32_e32 v57, 0xffff0000, v136
	v_lshlrev_b32_e32 v58, 16, v137
	v_and_b32_e32 v59, 0xffff0000, v137
	v_pk_mul_f32 v[12:13], v[108:109], v[12:13]
	v_pk_mul_f32 v[14:15], v[110:111], v[14:15]
	v_pk_mul_f32 v[12:13], v[12:13], v[56:57]
	v_pk_mul_f32 v[14:15], v[14:15], v[58:59]
	v_cvt_pk_bf16_f32 v12, v12, v13
	v_cvt_pk_bf16_f32 v13, v14, v15
	global_store_dwordx2 v[16:17], v[12:13], off offset:2240
	v_pk_mul_f32 v[8:9], v[8:9], v[24:25] op_sel_hi:[1,0]
	v_pk_mul_f32 v[10:11], v[10:11], v[24:25] op_sel_hi:[1,0]
	v_lshlrev_b32_e32 v40, 16, v138
	v_and_b32_e32 v41, 0xffff0000, v138
	v_lshlrev_b32_e32 v42, 16, v139
	v_and_b32_e32 v43, 0xffff0000, v139
	v_pk_mul_f32 v[8:9], v[112:113], v[8:9]
	v_pk_mul_f32 v[10:11], v[114:115], v[10:11]
	v_pk_mul_f32 v[8:9], v[8:9], v[40:41]
	v_pk_mul_f32 v[10:11], v[10:11], v[42:43]
	v_cvt_pk_bf16_f32 v8, v8, v9
	v_cvt_pk_bf16_f32 v9, v10, v11
	global_store_dwordx2 v[16:17], v[8:9], off offset:2272
	v_readlane_b32 s2, v254, 51
	v_readlane_b32 s0, v254, 27
	s_add_i32 s95, s95, s78
	s_add_i32 s2, s2, s0
	s_add_i32 s44, s44, s78
	s_cmpk_gt_i32 s95, 0xff
	s_cbranch_scc1 .LBB0_653
; #define LAS __attribute__((address_space(3)))
; template <bool DIFF>
; __device__ __forceinline__ void attn_item(LAS unsigned char* lds, const bf16_t* Z, bf16_t* MIX, int b, int h, int t, float lam, float shift, const float* gain, int tid, int wid, int lane) {
;     constexpr int NC = DIFF ? 2 : 1;
;     lane = lane_id(); asm volatile("" : "+v"(lane)); tid = wid * 64 + lane;
;     const int q16 = lane & 15, quad = lane >> 4;
;     const int row0 = b * SEQ + 128 * t + 16 * wid;
;     const int cq = 2 * t + (wid >> 2), nkt = 2 * t + 2;
;     const int qcol = DIFF ? (3072 + 128 * h) : (64 * h);
;     const int kcol = DIFF ? (4096 + 128 * h) : (512 + 64 * h);
;     const int vcol = DIFF ? (5120 + 128 * h) : (1024 + 128 * h);
;     const int gcol = DIFF ? (6144 + 128 * h) : (2048 + 128 * h);
;     const float lg = lg2gamma(h);
;     bf16x8 qf[NC][2];
;     { const bf16_t* qrow = Z + (size_t)(row0 + q16) * DIN + qcol;
; #pragma unroll
;       for (int c = 0; c < NC; ++c)
; #pragma unroll
;           for (int ds = 0; ds < 2; ++ds) qf[c][ds] = __builtin_nontemporal_load((const bf16x8*)(qrow + 64 * c + 32 * ds + 8 * quad)); }
;     f32x4 O[NC][8]; float l[NC];
; #pragma unroll
;     for (int c = 0; c < NC; ++c) { l[c] = 0.f;
; #pragma unroll
;         for (int eb = 0; eb < 8; ++eb) O[c][eb] = (f32x4){0.f, 0.f, 0.f, 0.f}; }
;     const char* kbase = (const char*)(Z + (size_t)(b * SEQ) * DIN + kcol);
;     const char* vbase = (const char*)(Z + (size_t)(b * SEQ) * DIN + vcol);
;     const unsigned krow = (unsigned)(8 * wid + (lane >> 3));
;     const unsigned kso = (krow * DIN + 8u * ((unsigned)(lane & 7) ^ (krow & 7u))) * 2u;
;     const unsigned vrow = (unsigned)(4 * wid + (lane >> 4));
;     const unsigned vso = (vrow * DIN + 8u * (2u * ((((unsigned)lane & 15u) >> 1) ^ (vrow & 7u)) + ((unsigned)lane & 1u))) * 2u;
;     constexpr int ATT_RING = 32768;
;     ...
;     asm volatile("s_waitcnt lgkmcnt(0)\n\ts_barrier" ::: "memory");
;     ATT_DMA(0, 0); ATT_DMA(1, 1);
;     ATT_WAITBAR_ONE();
;     const unsigned kfo = (unsigned)(q16 * 128), ksw = (unsigned)(q16 & 7);
; __global__ void __launch_bounds__(NWAVES * 64, 2) fwd(Args args) {
;     ...
;         for (int pi = vcu; pi < 256; pi += G) {
;             const int bh = pi >> 3, tp = pi & 7, b = bh >> 3, h = bh & 7;
;             attn_item<true>(lds, Z, MIX, b, h, 15 - tp, lam, shift, subln, 0, wid, 0);
.LBB0_565:
	v_writelane_b32 v254, s2, 51
	s_and_b32 s0, s2, 0xfffff800
	s_mul_hi_i32 s6, s0, 0x3800
	s_mul_i32 s7, s0, 0x3800
	v_readlane_b32 s0, v254, 25
	s_add_u32 s0, s0, s7
	v_readlane_b32 s1, v254, 26
	s_addc_u32 s1, s1, s6
	s_bfe_u32 s9, s95, 0x30003
	s_lshl_b32 s26, s9, 8
	s_add_u32 s76, s0, s26
	s_addc_u32 s77, s1, 0
	s_and_b32 s10, s95, 7
	s_xor_b32 s0, s10, 15
	s_lshl_b32 s1, s95, 5
	s_and_b32 s11, s1, 0xfffff800
	s_lshl_b32 s8, s0, 7
	v_mov_b32_e32 v8, v183
	s_or_b32 s1, s8, s11
	s_add_i32 s45, s1, s29
	v_and_b32_e32 v9, 15, v8
	v_or_b32_e32 v124, s45, v9
	v_mov_b64_e32 v[4:5], s[30:31]
	v_ashrrev_i32_e32 v10, 4, v8
	s_lshl_b32 s70, s0, 1
	v_mad_i64_i32 v[4:5], s[0:1], v124, s36, v[4:5]
	s_add_i32 s83, s70, s66
	s_lshl_b32 s80, s9, 7
	v_lshl_add_u64 v[126:127], v[4:5], 0, s[26:27]
	v_lshlrev_b32_e32 v4, 3, v10
	s_mul_i32 s1, s11, 0x3800
	v_ashrrev_i32_e32 v5, 31, v4
	s_mul_hi_i32 s0, s11, 0x3800
	s_add_u32 s12, s30, s1
	v_lshl_add_u64 v[4:5], v[4:5], 1, v[126:127]
	s_addc_u32 s13, s31, s0
	v_lshl_add_u64 v[6:7], v[4:5], 0, s[14:15]
	v_add_co_u32_e32 v4, vcc, s16, v4
	s_add_u32 s71, s12, s26
	s_nop 0
	v_addc_co_u32_e32 v5, vcc, 0, v5, vcc
	global_load_dwordx4 v[76:79], v[6:7], off offset:64 nt
	global_load_dwordx4 v[72:75], v[6:7], off offset:128 nt
	global_load_dwordx4 v[80:83], v[4:5], off offset:2048 nt
	global_load_dwordx4 v[68:71], v[6:7], off offset:192 nt
	s_addc_u32 s94, s13, 0
	v_ashrrev_i32_e32 v4, 3, v8
	s_add_u32 s0, s71, 0x2000
	v_add_u32_e32 v5, s34, v4
	v_xor_b32_e32 v4, v4, v8
	s_addc_u32 s1, s94, 0
	v_mul_lo_u32 v5, v5, s37
	v_lshlrev_b32_e32 v4, 3, v4
	s_add_u32 s2, s71, 0x2800
	v_and_or_b32 v4, v4, 56, v5
	v_writelane_b32 v254, s0, 52
	s_addc_u32 s3, s94, 0
	v_lshlrev_b32_e32 v180, 1, v4
	v_add_u32_e32 v4, s35, v10
	v_writelane_b32 v254, s1, 53
	v_lshlrev_b32_e32 v5, 1, v4
	v_writelane_b32 v254, s2, 54
	v_xor_b32_e32 v5, v5, v8
	v_and_b32_e32 v6, 1, v8
	s_waitcnt lgkmcnt(0)
	s_barrier
	v_writelane_b32 v254, s3, 55
	s_add_u32 s4, s2, 0x70000
	s_mov_b32 m0, s90
	v_and_or_b32 v6, v5, 14, v6
	v_mul_lo_u32 v7, v4, s36
	s_addc_u32 s5, s3, 0
	v_lshl_add_u64 v[4:5], s[0:1], 0, v[180:181]
	global_load_lds_dwordx4 v180, s[0:1]
	v_lshl_add_u64 v[4:5], v[4:5], 0, s[96:97]
	s_mov_b32 m0, s17
	v_lshl_or_b32 v132, v6, 4, v7
	global_load_lds_dwordx4 v[4:5], off
	s_mov_b32 m0, s43
	s_add_u32 s0, s71, 0xe2000
	global_load_lds_dwordx4 v132, s[2:3]
	s_mov_b32 m0, s38
	s_addc_u32 s1, s94, 0
	global_load_lds_dwordx4 v132, s[4:5]
	v_writelane_b32 v254, s0, 56
	s_add_u32 s4, s71, 0xe2800
	s_addc_u32 s5, s94, 0
	v_writelane_b32 v254, s1, 57
	v_writelane_b32 v254, s4, 58
	s_mov_b32 m0, s39
	v_lshl_add_u64 v[4:5], s[0:1], 0, v[180:181]
	v_writelane_b32 v254, s5, 59
	s_add_u32 s14, s4, 0x70000
	s_addc_u32 s15, s5, 0
	global_load_lds_dwordx4 v180, s[0:1]
	v_lshl_add_u64 v[4:5], v[4:5], 0, s[96:97]
	s_mov_b32 m0, s18
	v_lshlrev_b32_e32 v128, 2, v10
	global_load_lds_dwordx4 v[4:5], off
	s_mov_b32 m0, s40
	v_bfe_u32 v4, v8, 2, 2
	global_load_lds_dwordx4 v132, s[4:5]
	s_mov_b32 m0, s41
	v_lshlrev_b32_e32 v6, 3, v8
	global_load_lds_dwordx4 v132, s[14:15]
	v_or_b32_e32 v4, v128, v4
	v_and_b32_e32 v6, 24, v6
	v_lshlrev_b32_e32 v5, 5, v4
	v_lshl_or_b32 v4, v4, 8, v6
	v_add_u32_e32 v143, 0x4000, v4
	v_bitop3_b32 v4, v10, v8, 7 bitop3:0x78
	v_lshlrev_b32_e32 v145, 4, v4
	v_add_u32_e32 v4, 4, v10
	s_waitcnt vmcnt(4) lgkmcnt(0)
	s_barrier
	v_bitop3_b32 v4, v4, v8, 7 bitop3:0x78
	v_mov_b32_e32 v6, v181
	v_mov_b32_e32 v7, v181
	v_lshlrev_b32_e32 v144, 7, v9
	v_and_b32_e32 v142, 0xe0, v5
	v_lshlrev_b32_e32 v146, 4, v4
	v_bitop3_b32 v141, v5, 32, v186 bitop3:0x6c
	v_bitop3_b32 v140, v5, 64, v186 bitop3:0x6c
	v_bitop3_b32 v139, v5, s73, v186 bitop3:0x6c
	v_bitop3_b32 v138, v5, s74, v186 bitop3:0x6c
	v_bitop3_b32 v137, v5, s75, v186 bitop3:0x6c
	v_bitop3_b32 v136, v5, s79, v186 bitop3:0x6c
	v_bitop3_b32 v129, v5, s67, v5 bitop3:0xc
	v_mov_b32_e32 v4, v181
	v_mov_b32_e32 v5, v181
	v_mov_b64_e32 v[14:15], v[6:7]
	v_mov_b64_e32 v[22:23], v[6:7]
	v_mov_b64_e32 v[30:31], v[6:7]
	v_mov_b64_e32 v[38:39], v[6:7]
	v_mov_b64_e32 v[46:47], v[6:7]
	v_mov_b64_e32 v[54:55], v[6:7]
	v_mov_b64_e32 v[58:59], v[6:7]
	v_mov_b64_e32 v[10:11], v[6:7]
	v_mov_b64_e32 v[18:19], v[6:7]
	v_mov_b64_e32 v[26:27], v[6:7]
	v_mov_b64_e32 v[34:35], v[6:7]
	v_mov_b64_e32 v[42:43], v[6:7]
	v_mov_b64_e32 v[50:51], v[6:7]
	v_mov_b64_e32 v[62:63], v[6:7]
	v_mov_b64_e32 v[66:67], v[6:7]
	v_ashrrev_i32_e32 v125, 31, v124
	s_mov_b32 s17, 0
	v_mov_b32_e32 v133, v181
	v_mov_b32_e32 v130, v181
	v_mov_b32_e32 v131, v181
	s_mov_b64 s[4:5], s[76:77]
	v_mov_b64_e32 v[12:13], v[4:5]
	v_mov_b64_e32 v[20:21], v[4:5]
	v_mov_b64_e32 v[28:29], v[4:5]
	v_mov_b64_e32 v[36:37], v[4:5]
	v_mov_b64_e32 v[44:45], v[4:5]
	v_mov_b64_e32 v[52:53], v[4:5]
	v_mov_b64_e32 v[56:57], v[4:5]
	v_mov_b64_e32 v[8:9], v[4:5]
	v_mov_b64_e32 v[16:17], v[4:5]
	v_mov_b64_e32 v[24:25], v[4:5]
	v_mov_b64_e32 v[32:33], v[4:5]
	v_mov_b64_e32 v[40:41], v[4:5]
	v_mov_b64_e32 v[48:49], v[4:5]
	v_mov_b64_e32 v[60:61], v[4:5]
	s_mov_b32 s15, 0
	v_mov_b64_e32 v[64:65], v[4:5]
	s_waitcnt vmcnt(0)

; template <bool DIFF>
; __device__ __forceinline__ void attn_item(LAS unsigned char* lds, const bf16_t* Z, bf16_t* MIX, int b, int h, int t, float lam, float shift, const float* gain, int tid, int wid, int lane) {
;     ...
;     float inv0 = 1.f, inv1 = 0.f;
;     if (DIFF) {
; #pragma unroll
;         for (int c = 0; c < NC; ++c) l[c] = quad_sum(l[c]);
;         inv0 = 1.0f / l[0]; inv1 = lam / l[NC - 1];
;     }
;     float ss = 0.f;
; #pragma unroll
;     for (int eb = 0; eb < 8; ++eb)
; #pragma unroll
;         for (int i = 0; i < 4; ++i) { float v = O[0][eb][i] * inv0; if (DIFF) v -= O[NC - 1][eb][i] * inv1; O[0][eb][i] = v; ss += v * v; }
;     ss = quad_sum(ss);
;     const float r = rsqrtf(ss * (1.0f / 128.0f) + EPS) * (DIFF ? 0.8f : 1.0f);
;     const int row = row0 + q16;
;     const bf16_t* gp = Z + (size_t)row * DIN + gcol + 4 * quad;
;     bf16_t* op = MIX + (size_t)row * DM + (DIFF ? 1024 : 0) + 128 * h + 4 * quad;
.LBB0_574:
	s_waitcnt lgkmcnt(0)
	ds_swizzle_b32 v68, v131 offset:swizzle(SWAP,16)
	ds_swizzle_b32 v69, v130 offset:swizzle(SWAP,16)
	v_ashrrev_i32_e32 v129, 31, v128
	v_lshlrev_b64 v[80:81], 1, v[128:129]
	s_lshl_b32 s86, s80, 1
	s_waitcnt lgkmcnt(0)
	v_add_f32_e32 v68, v131, v68
	v_mov_b32_e32 v70, v68
	s_nop 1
	v_permlane32_swap_b32_e32 v68, v70
	v_add_f32_e32 v68, v68, v70
	v_div_scale_f32 v70, s[0:1], v68, v68, 1.0
	v_rcp_f32_e32 v72, v70
	v_add_f32_e32 v69, v130, v69
	v_mov_b32_e32 v71, v69
	s_nop 1
	v_permlane32_swap_b32_e32 v69, v71
	v_add_f32_e32 v69, v69, v71
	v_fma_f32 v71, -v70, v72, 1.0
	v_fmac_f32_e32 v72, v71, v72
	v_div_scale_f32 v71, vcc, 1.0, v68, 1.0
	v_mul_f32_e32 v73, v71, v72
	v_fma_f32 v74, -v70, v73, v71
	v_fmac_f32_e32 v73, v74, v72
	v_fma_f32 v70, -v70, v73, v71
	v_div_scale_f32 v71, s[0:1], v69, v69, s28
	v_rcp_f32_e32 v74, v71
	v_div_fmas_f32 v70, v70, v72, v73
	v_div_fixup_f32 v76, v70, v68, 1.0
	s_movk_i32 s0, 0x3000
	v_fma_f32 v68, -v71, v74, 1.0
	v_fmac_f32_e32 v74, v68, v74
	v_div_scale_f32 v68, vcc, s28, v69, s28
	v_mul_f32_e32 v70, v68, v74
	v_fma_f32 v72, -v71, v70, v68
	v_fmac_f32_e32 v70, v72, v74
	v_fma_f32 v68, -v71, v70, v68
	v_lshl_add_u64 v[72:73], v[126:127], 0, v[80:81]
	v_div_fmas_f32 v68, v68, v74, v70
	v_lshl_add_u64 v[70:71], v[72:73], 0, s[92:93]
	v_add_co_u32_e32 v72, vcc, s0, v72
	v_div_fixup_f32 v78, v68, v69, s28
	v_lshlrev_b64 v[68:69], 12, v[124:125]
	v_addc_co_u32_e32 v73, vcc, 0, v73, vcc
	v_lshl_add_u64 v[82:83], s[88:89], 0, v[68:69]
	v_lshl_add_u64 v[68:69], v[128:129], 2, s[84:85]
	global_load_dwordx2 v[116:117], v[70:71], off
	global_load_dwordx4 v[84:87], v[68:69], off
	global_load_dwordx2 v[118:119], v[70:71], off offset:32
	global_load_dwordx4 v[88:91], v[68:69], off offset:64
	global_load_dwordx2 v[120:121], v[70:71], off offset:64
	global_load_dwordx4 v[92:95], v[68:69], off offset:128
	global_load_dwordx2 v[122:123], v[70:71], off offset:96
	global_load_dwordx4 v[96:99], v[68:69], off offset:192
	global_load_dwordx2 v[132:133], v[70:71], off offset:128
	global_load_dwordx4 v[100:103], v[68:69], off offset:256
	global_load_dwordx2 v[134:135], v[70:71], off offset:160
	global_load_dwordx4 v[104:107], v[68:69], off offset:320
	global_load_dwordx2 v[136:137], v[70:71], off offset:192
	global_load_dwordx4 v[108:111], v[68:69], off offset:384
	global_load_dwordx2 v[138:139], v[70:71], off offset:224
	global_load_dwordx4 v[112:115], v[68:69], off offset:448
	v_pk_mul_f32 v[56:57], v[56:57], v[78:79] op_sel_hi:[1,0]
	v_pk_mul_f32 v[58:59], v[58:59], v[78:79] op_sel_hi:[1,0]
	v_pk_fma_f32 v[56:57], v[64:65], v[76:77], v[56:57] op_sel_hi:[1,0,1] neg_lo:[0,0,1] neg_hi:[0,0,1]
	v_pk_fma_f32 v[58:59], v[66:67], v[76:77], v[58:59] op_sel_hi:[1,0,1] neg_lo:[0,0,1] neg_hi:[0,0,1]
	v_pk_mul_f32 v[64:65], v[56:57], v[56:57]
	v_pk_mul_f32 v[66:67], v[58:59], v[58:59]
	v_pk_mul_f32 v[52:53], v[52:53], v[78:79] op_sel_hi:[1,0]
	v_add_f32_e32 v64, v64, v65
	v_pk_fma_f32 v[52:53], v[60:61], v[76:77], v[52:53] op_sel_hi:[1,0,1] neg_lo:[0,0,1] neg_hi:[0,0,1]
	v_add_f32_e32 v64, v66, v64
	v_pk_mul_f32 v[54:55], v[54:55], v[78:79] op_sel_hi:[1,0]
	v_pk_mul_f32 v[60:61], v[52:53], v[52:53]
	v_add_f32_e32 v64, v67, v64
	v_pk_fma_f32 v[54:55], v[62:63], v[76:77], v[54:55] op_sel_hi:[1,0,1] neg_lo:[0,0,1] neg_hi:[0,0,1]
	v_add_f32_e32 v60, v60, v64
	v_pk_mul_f32 v[62:63], v[54:55], v[54:55]
	v_pk_mul_f32 v[44:45], v[44:45], v[78:79] op_sel_hi:[1,0]
	v_add_f32_e32 v60, v61, v60
	v_pk_fma_f32 v[44:45], v[48:49], v[76:77], v[44:45] op_sel_hi:[1,0,1] neg_lo:[0,0,1] neg_hi:[0,0,1]
	v_add_f32_e32 v60, v62, v60
	v_pk_mul_f32 v[46:47], v[46:47], v[78:79] op_sel_hi:[1,0]
	v_pk_mul_f32 v[48:49], v[44:45], v[44:45]
	v_add_f32_e32 v60, v63, v60
	v_pk_fma_f32 v[46:47], v[50:51], v[76:77], v[46:47] op_sel_hi:[1,0,1] neg_lo:[0,0,1] neg_hi:[0,0,1]
	v_add_f32_e32 v48, v48, v60
	v_pk_mul_f32 v[50:51], v[46:47], v[46:47]
	v_pk_mul_f32 v[36:37], v[36:37], v[78:79] op_sel_hi:[1,0]
	v_add_f32_e32 v48, v49, v48
	v_pk_fma_f32 v[36:37], v[40:41], v[76:77], v[36:37] op_sel_hi:[1,0,1] neg_lo:[0,0,1] neg_hi:[0,0,1]
	v_add_f32_e32 v48, v50, v48
	v_pk_mul_f32 v[38:39], v[38:39], v[78:79] op_sel_hi:[1,0]
	v_pk_mul_f32 v[40:41], v[36:37], v[36:37]
	v_add_f32_e32 v48, v51, v48
	v_pk_fma_f32 v[38:39], v[42:43], v[76:77], v[38:39] op_sel_hi:[1,0,1] neg_lo:[0,0,1] neg_hi:[0,0,1]
	v_add_f32_e32 v40, v40, v48
	v_pk_mul_f32 v[42:43], v[38:39], v[38:39]
	v_pk_mul_f32 v[28:29], v[28:29], v[78:79] op_sel_hi:[1,0]
	v_add_f32_e32 v40, v41, v40
	v_pk_fma_f32 v[28:29], v[32:33], v[76:77], v[28:29] op_sel_hi:[1,0,1] neg_lo:[0,0,1] neg_hi:[0,0,1]
	v_add_f32_e32 v40, v42, v40
	v_pk_mul_f32 v[30:31], v[30:31], v[78:79] op_sel_hi:[1,0]
	v_pk_mul_f32 v[32:33], v[28:29], v[28:29]
	v_add_f32_e32 v40, v43, v40
	v_pk_fma_f32 v[30:31], v[34:35], v[76:77], v[30:31] op_sel_hi:[1,0,1] neg_lo:[0,0,1] neg_hi:[0,0,1]
	v_add_f32_e32 v32, v32, v40
	v_pk_mul_f32 v[34:35], v[30:31], v[30:31]
	v_pk_mul_f32 v[20:21], v[20:21], v[78:79] op_sel_hi:[1,0]
	v_add_f32_e32 v32, v33, v32
	v_pk_fma_f32 v[20:21], v[24:25], v[76:77], v[20:21] op_sel_hi:[1,0,1] neg_lo:[0,0,1] neg_hi:[0,0,1]
	v_add_f32_e32 v32, v34, v32
	v_pk_mul_f32 v[22:23], v[22:23], v[78:79] op_sel_hi:[1,0]
	v_pk_mul_f32 v[24:25], v[20:21], v[20:21]
	v_add_f32_e32 v32, v35, v32
	v_pk_fma_f32 v[22:23], v[26:27], v[76:77], v[22:23] op_sel_hi:[1,0,1] neg_lo:[0,0,1] neg_hi:[0,0,1]
	v_add_f32_e32 v24, v24, v32
	v_pk_mul_f32 v[26:27], v[22:23], v[22:23]
	v_pk_mul_f32 v[12:13], v[12:13], v[78:79] op_sel_hi:[1,0]
	v_add_f32_e32 v24, v25, v24
	v_pk_fma_f32 v[12:13], v[16:17], v[76:77], v[12:13] op_sel_hi:[1,0,1] neg_lo:[0,0,1] neg_hi:[0,0,1]
	v_add_f32_e32 v24, v26, v24
	v_pk_mul_f32 v[14:15], v[14:15], v[78:79] op_sel_hi:[1,0]
	v_pk_mul_f32 v[16:17], v[12:13], v[12:13]
	v_add_f32_e32 v24, v27, v24
	v_pk_fma_f32 v[14:15], v[18:19], v[76:77], v[14:15] op_sel_hi:[1,0,1] neg_lo:[0,0,1] neg_hi:[0,0,1]
	v_add_f32_e32 v16, v16, v24
	v_pk_mul_f32 v[18:19], v[14:15], v[14:15]
	v_pk_mul_f32 v[4:5], v[4:5], v[78:79] op_sel_hi:[1,0]
	v_add_f32_e32 v16, v17, v16
	v_pk_fma_f32 v[8:9], v[8:9], v[76:77], v[4:5] op_sel_hi:[1,0,1] neg_lo:[0,0,1] neg_hi:[0,0,1]
	v_add_f32_e32 v16, v18, v16
	v_pk_mul_f32 v[6:7], v[6:7], v[78:79] op_sel_hi:[1,0]
	v_pk_mul_f32 v[4:5], v[8:9], v[8:9]
	v_add_f32_e32 v16, v19, v16
	v_pk_fma_f32 v[10:11], v[10:11], v[76:77], v[6:7] op_sel_hi:[1,0,1] neg_lo:[0,0,1] neg_hi:[0,0,1]
	v_add_f32_e32 v4, v4, v16
	v_pk_mul_f32 v[6:7], v[10:11], v[10:11]
	v_add_f32_e32 v4, v5, v4
	v_add_f32_e32 v4, v6, v4
	v_add_f32_e32 v6, v7, v4
	ds_swizzle_b32 v7, v6 offset:swizzle(SWAP,16)
	v_mov_b32_e32 v18, 0x358637bd
	s_mov_b32 s87, s27
	v_lshl_add_u64 v[4:5], v[82:83], 0, s[86:87]
	v_lshl_add_u64 v[16:17], v[4:5], 0, v[80:81]
	s_waitcnt lgkmcnt(0)
; __device__ __forceinline__ unsigned cvtpk(float lo, float hi) { f32x2 v = {lo, hi}; bf16x2_t b = __builtin_convertvector(v, bf16x2_t); return __builtin_bit_cast(unsigned, b); }
; __device__ __forceinline__ float bflo(unsigned u) { return __uint_as_float(u << 16); }
; __device__ __forceinline__ float bfhi(unsigned u) { return __uint_as_float(u & 0xffff0000u); }
; template <bool DIFF>
; __device__ __forceinline__ void attn_item(LAS unsigned char* lds, const bf16_t* Z, bf16_t* MIX, int b, int h, int t, float lam, float shift, const float* gain, int tid, int wid, int lane) {
;     ...
;     ss = quad_sum(ss);
;     const float r = rsqrtf(ss * (1.0f / 128.0f) + EPS) * (DIFF ? 0.8f : 1.0f);
;     const int row = row0 + q16;
;     const bf16_t* gp = Z + (size_t)row * DIN + gcol + 4 * quad;
;     bf16_t* op = MIX + (size_t)row * DM + (DIFF ? 1024 : 0) + 128 * h + 4 * quad;
; #pragma unroll
;     for (int eb = 0; eb < 8; ++eb) {
;         const u32x2 gw = *(const u32x2*)(gp + 16 * eb);
;         const f32x4 gn = *(const f32x4*)(gain + 16 * eb + 4 * quad);
;         u32x2 w; w.x = cvtpk(O[0][eb][0] * r * gn.x * bflo(gw.x), O[0][eb][1] * r * gn.y * bfhi(gw.x));
;         w.y = cvtpk(O[0][eb][2] * r * gn.z * bflo(gw.y), O[0][eb][3] * r * gn.w * bfhi(gw.y));
;         *(u32x2*)(op + 16 * eb) = w;
;     }
	v_add_f32_e32 v6, v6, v7
	v_mov_b32_e32 v7, v6
	s_nop 1
	v_permlane32_swap_b32_e32 v6, v7
	v_add_f32_e32 v6, v6, v7
	v_fmamk_f32 v6, v6, 0x3c000000, v18
	v_mul_f32_e32 v7, 0x4b800000, v6
	v_cmp_gt_f32_e32 vcc, s42, v6
	s_nop 1
	v_cndmask_b32_e32 v6, v6, v7, vcc
	v_rsq_f32_e32 v24, v6
	s_nop 0
	v_mul_f32_e32 v25, 0x45800000, v24
	v_cndmask_b32_e32 v24, v24, v25, vcc
	v_mul_f32_e32 v24, 0x3f4ccccd, v24
	s_waitcnt vmcnt(0)
	v_pk_mul_f32 v[56:57], v[56:57], v[24:25] op_sel_hi:[1,0]
	v_pk_mul_f32 v[58:59], v[58:59], v[24:25] op_sel_hi:[1,0]
	v_lshlrev_b32_e32 v60, 16, v116
	v_and_b32_e32 v61, 0xffff0000, v116
	v_lshlrev_b32_e32 v62, 16, v117
	v_and_b32_e32 v63, 0xffff0000, v117
	v_pk_mul_f32 v[56:57], v[84:85], v[56:57]
	v_pk_mul_f32 v[58:59], v[86:87], v[58:59]
	v_pk_mul_f32 v[56:57], v[56:57], v[60:61]
	v_pk_mul_f32 v[58:59], v[58:59], v[62:63]
	v_cvt_pk_bf16_f32 v56, v56, v57
	v_cvt_pk_bf16_f32 v57, v58, v59
	global_store_dwordx2 v[16:17], v[56:57], off offset:2048
	v_pk_mul_f32 v[52:53], v[52:53], v[24:25] op_sel_hi:[1,0]
	v_pk_mul_f32 v[54:55], v[54:55], v[24:25] op_sel_hi:[1,0]
	v_lshlrev_b32_e32 v40, 16, v118
	v_and_b32_e32 v41, 0xffff0000, v118
	v_lshlrev_b32_e32 v42, 16, v119
	v_and_b32_e32 v43, 0xffff0000, v119
	v_pk_mul_f32 v[52:53], v[88:89], v[52:53]
	v_pk_mul_f32 v[54:55], v[90:91], v[54:55]
	v_pk_mul_f32 v[52:53], v[52:53], v[40:41]
	v_pk_mul_f32 v[54:55], v[54:55], v[42:43]
	v_cvt_pk_bf16_f32 v52, v52, v53
	v_cvt_pk_bf16_f32 v53, v54, v55
	global_store_dwordx2 v[16:17], v[52:53], off offset:2080
	v_pk_mul_f32 v[44:45], v[44:45], v[24:25] op_sel_hi:[1,0]
	v_pk_mul_f32 v[46:47], v[46:47], v[24:25] op_sel_hi:[1,0]
	v_lshlrev_b32_e32 v60, 16, v120
	v_and_b32_e32 v61, 0xffff0000, v120
	v_lshlrev_b32_e32 v62, 16, v121
	v_and_b32_e32 v63, 0xffff0000, v121
	v_pk_mul_f32 v[44:45], v[92:93], v[44:45]
	v_pk_mul_f32 v[46:47], v[94:95], v[46:47]
	v_pk_mul_f32 v[44:45], v[44:45], v[60:61]
	v_pk_mul_f32 v[46:47], v[46:47], v[62:63]
	v_cvt_pk_bf16_f32 v44, v44, v45
	v_cvt_pk_bf16_f32 v45, v46, v47
	global_store_dwordx2 v[16:17], v[44:45], off offset:2112
	v_pk_mul_f32 v[36:37], v[36:37], v[24:25] op_sel_hi:[1,0]
	v_pk_mul_f32 v[38:39], v[38:39], v[24:25] op_sel_hi:[1,0]
	v_lshlrev_b32_e32 v40, 16, v122
	v_and_b32_e32 v41, 0xffff0000, v122
	v_lshlrev_b32_e32 v42, 16, v123
	v_and_b32_e32 v43, 0xffff0000, v123
	v_pk_mul_f32 v[36:37], v[96:97], v[36:37]
	v_pk_mul_f32 v[38:39], v[98:99], v[38:39]
	v_pk_mul_f32 v[36:37], v[36:37], v[40:41]
	v_pk_mul_f32 v[38:39], v[38:39], v[42:43]
	v_cvt_pk_bf16_f32 v36, v36, v37
	v_cvt_pk_bf16_f32 v37, v38, v39
	global_store_dwordx2 v[16:17], v[36:37], off offset:2144
	v_pk_mul_f32 v[28:29], v[28:29], v[24:25] op_sel_hi:[1,0]
	v_pk_mul_f32 v[30:31], v[30:31], v[24:25] op_sel_hi:[1,0]
	v_lshlrev_b32_e32 v60, 16, v132
	v_and_b32_e32 v61, 0xffff0000, v132
	v_lshlrev_b32_e32 v62, 16, v133
	v_and_b32_e32 v63, 0xffff0000, v133
	v_pk_mul_f32 v[28:29], v[100:101], v[28:29]
	v_pk_mul_f32 v[30:31], v[102:103], v[30:31]
	v_pk_mul_f32 v[28:29], v[28:29], v[60:61]
	v_pk_mul_f32 v[30:31], v[30:31], v[62:63]
	v_cvt_pk_bf16_f32 v28, v28, v29
	v_cvt_pk_bf16_f32 v29, v30, v31
	global_store_dwordx2 v[16:17], v[28:29], off offset:2176
	v_pk_mul_f32 v[20:21], v[20:21], v[24:25] op_sel_hi:[1,0]
	v_pk_mul_f32 v[22:23], v[22:23], v[24:25] op_sel_hi:[1,0]
	v_lshlrev_b32_e32 v40, 16, v134
	v_and_b32_e32 v41, 0xffff0000, v134
	v_lshlrev_b32_e32 v42, 16, v135
	v_and_b32_e32 v43, 0xffff0000, v135
	v_pk_mul_f32 v[20:21], v[104:105], v[20:21]
	v_pk_mul_f32 v[22:23], v[106:107], v[22:23]
	v_pk_mul_f32 v[20:21], v[20:21], v[40:41]
	v_pk_mul_f32 v[22:23], v[22:23], v[42:43]
	v_cvt_pk_bf16_f32 v20, v20, v21
	v_cvt_pk_bf16_f32 v21, v22, v23
	global_store_dwordx2 v[16:17], v[20:21], off offset:2208
	v_pk_mul_f32 v[12:13], v[12:13], v[24:25] op_sel_hi:[1,0]
	v_pk_mul_f32 v[14:15], v[14:15], v[24:25] op_sel_hi:[1,0]
	v_lshlrev_b32_e32 v60, 16, v136
	v_and_b32_e32 v61, 0xffff0000, v136
	v_lshlrev_b32_e32 v62, 16, v137
	v_and_b32_e32 v63, 0xffff0000, v137
	v_pk_mul_f32 v[12:13], v[108:109], v[12:13]
	v_pk_mul_f32 v[14:15], v[110:111], v[14:15]
	v_pk_mul_f32 v[12:13], v[12:13], v[60:61]
	v_pk_mul_f32 v[14:15], v[14:15], v[62:63]
	v_cvt_pk_bf16_f32 v12, v12, v13
	v_cvt_pk_bf16_f32 v13, v14, v15
	global_store_dwordx2 v[16:17], v[12:13], off offset:2240
	v_pk_mul_f32 v[8:9], v[8:9], v[24:25] op_sel_hi:[1,0]
	v_pk_mul_f32 v[10:11], v[10:11], v[24:25] op_sel_hi:[1,0]
	v_lshlrev_b32_e32 v40, 16, v138
	v_and_b32_e32 v41, 0xffff0000, v138
	v_lshlrev_b32_e32 v42, 16, v139
	v_and_b32_e32 v43, 0xffff0000, v139
	v_pk_mul_f32 v[8:9], v[112:113], v[8:9]
	v_pk_mul_f32 v[10:11], v[114:115], v[10:11]
	v_pk_mul_f32 v[8:9], v[8:9], v[40:41]
	v_pk_mul_f32 v[10:11], v[10:11], v[42:43]
	v_cvt_pk_bf16_f32 v8, v8, v9
	v_cvt_pk_bf16_f32 v9, v10, v11
	global_store_dwordx2 v[16:17], v[8:9], off offset:2272
	v_mov_b32_e32 v15, v183
	s_cmp_lt_i32 s9, 3
	s_cbranch_scc1 .LBB0_579
	s_cmp_lt_i32 s9, 4
	s_cbranch_scc1 .LBB0_580
	s_cmp_lt_i32 s9, 5
	s_cbranch_scc1 .LBB0_581
	s_cmp_lg_u32 s9, 5
	s_cbranch_scc0 .LBB0_582
	s_cmp_eq_u32 s9, 6
	s_cselect_b64 vcc, -1, 0
	v_mov_b32_e32 v4, 0xba38b001
	v_mov_b32_e32 v5, 0xbab8b5c7
	v_cndmask_b32_e32 v12, v4, v5, vcc
	s_cbranch_execz .LBB0_583
	s_branch .LBB0_584

; #define LAS __attribute__((address_space(3)))
; __device__ __forceinline__ void ret_pair(LAS unsigned char* lds, const bf16_t* Z, bf16_t* MIX, int b, int h, int tA, int tB, const float* gain, int wid) {
;     int lane = lane_id(); asm volatile("" : "+v"(lane));
;     const int q16 = lane & 15, quad = lane >> 4;
;     const int rowA0 = b * SEQ + 128 * tA + 16 * wid, rowB0 = b * SEQ + 128 * tB + 16 * wid;
;     const int cqA = 2 * tA + (wid >> 2), cqB = 2 * tB + (wid >> 2), nkt = 2 * tA + 2;
;     const int qcol = 64 * h, kcol = 512 + 64 * h, vcol = 1024 + 128 * h, gcol = 2048 + 128 * h;
;     const float lg = lg2gamma(h);
;     bf16x8 qfA[2], qfB[2];
;     { const bf16_t* qa = Z + (size_t)(rowA0 + q16) * DIN + qcol; const bf16_t* qb = Z + (size_t)(rowB0 + q16) * DIN + qcol;
; #pragma unroll
;       for (int ds = 0; ds < 2; ++ds) { qfA[ds] = __builtin_nontemporal_load((const bf16x8*)(qa + 32 * ds + 8 * quad)); qfB[ds] = __builtin_nontemporal_load((const bf16x8*)(qb + 32 * ds + 8 * quad)); } }
;     f32x4 OA[8], OB[8];
; #pragma unroll
;     for (int eb = 0; eb < 8; ++eb) { OA[eb] = (f32x4){0.f, 0.f, 0.f, 0.f}; OB[eb] = OA[eb]; }
;     const char* kbase = (const char*)(Z + (size_t)(b * SEQ) * DIN + kcol);
;     const char* vbase = (const char*)(Z + (size_t)(b * SEQ) * DIN + vcol);
;     const unsigned krow = (unsigned)(8 * wid + (lane >> 3));
;     const unsigned kso = (krow * DIN + 8u * ((unsigned)(lane & 7) ^ (krow & 7u))) * 2u;
;     const unsigned vrow = (unsigned)(4 * wid + (lane >> 4));
;     const unsigned vso = (vrow * DIN + 8u * (2u * ((((unsigned)lane & 15u) >> 1) ^ (vrow & 7u)) + ((unsigned)lane & 1u))) * 2u;
;     constexpr int RING = 32768;
;     ...
;     asm volatile("s_waitcnt lgkmcnt(0)\n\ts_barrier" ::: "memory");
;     RP_DMA(0, 0); RP_DMA(1, 1);
;     asm volatile("s_waitcnt vmcnt(3) lgkmcnt(0)\n\ts_barrier" ::: "memory");
;     const unsigned kfo = (unsigned)(q16 * 128), ksw = (unsigned)(q16 & 7);
;     const unsigned vrr = (unsigned)(4 * quad + (q16 >> 2)), vx32 = (vrr & 7u) * 32u, vb0 = 16384u + vrr * 256u + 8u * (unsigned)(q16 & 3);
;     const float iqA = (float)(128 * tA + 16 * wid + q16), iqB = (float)(128 * tB + 16 * wid + q16);
; __global__ void __launch_bounds__(NWAVES * 64, 2) fwd(Args args) {
;     ...
;             ret_pair(lds, Z, MIX, b, h, 15 - tp, tp, ret_gn + 128 * h, wid);
.LBB0_595:
	s_lshl_b32 s14, s10, 8
	s_or_b32 s0, s14, s11
	v_writelane_b32 v255, s95, 1
	s_add_i32 s5, s0, s29
	s_add_i32 s8, s14, 0x80
	s_or_b32 s45, s8, s11
	s_add_i32 s45, s45, s29
	s_lshl_b32 s82, s10, 2
	s_add_i32 s70, s82, 2
	s_add_i32 s83, s70, s66
	s_add_i32 s0, s70, -1
	s_cmp_lt_u32 s0, s83
	s_cselect_b64 s[2:3], -1, 0
	v_writelane_b32 v254, s2, 60
	v_writelane_b32 v254, s3, 61
	v_writelane_b32 v254, s0, 62
	s_cmp_lt_u32 s70, s83
	s_cselect_b64 s[2:3], -1, 0
	v_writelane_b32 v254, s2, 63
	v_writelane_b32 v255, s3, 0
	s_and_b32 s0, s44, 7
	v_writelane_b32 v255, s44, 2
	s_lshl_b32 s0, s0, 2
	s_add_i32 s91, s82, s66
	v_writelane_b32 v255, s0, 3
	s_add_i32 s72, s66, s0
	v_readlane_b32 s0, v254, 28
	s_add_u32 s0, s0, s7
	v_readlane_b32 s1, v254, 29
	s_addc_u32 s1, s1, s6
	s_add_u32 s2, s0, s26
	s_addc_u32 s3, s1, 0
	v_readlane_b32 s0, v254, 30
	s_add_u32 s0, s0, s7
	v_readlane_b32 s1, v254, 31
	v_and_b32_e32 v14, 15, v15
	s_addc_u32 s1, s1, s6
	s_lshl_b32 s4, s9, 7
	s_add_u32 s84, s0, s4
	v_or_b32_e32 v6, s45, v14
	v_mov_b64_e32 v[4:5], s[30:31]
	s_addc_u32 s85, s1, 0
	v_mad_i64_i32 v[6:7], s[0:1], v6, s36, v[4:5]
	v_writelane_b32 v255, s45, 4
	s_mov_b32 s1, s27
	v_writelane_b32 v255, s0, 5
	v_or_b32_e32 v8, s5, v14
	s_mov_b32 s81, s27
	v_writelane_b32 v255, s1, 6
	v_mad_i64_i32 v[4:5], s[0:1], v8, s36, v[4:5]
	s_add_u32 s9, s12, s80
	v_ashrrev_i32_e32 v13, 3, v15
	v_ashrrev_i32_e32 v17, 4, v15
	v_lshl_add_u64 v[6:7], v[6:7], 0, s[80:81]
	v_lshl_add_u64 v[4:5], v[4:5], 0, s[80:81]
	s_addc_u32 s81, s13, 0
	v_add_u32_e32 v16, s34, v13
	v_xor_b32_e32 v13, v13, v15
	v_lshlrev_b32_e32 v8, 3, v17
	s_add_u32 s4, s9, 0x400
	v_mul_lo_u32 v16, v16, s37
	v_lshlrev_b32_e32 v13, 3, v13
	v_writelane_b32 v255, s5, 7
	v_ashrrev_i32_e32 v9, 31, v8
	s_addc_u32 s5, s81, 0
	v_and_or_b32 v13, v13, 56, v16
	v_lshlrev_b64 v[8:9], 1, v[8:9]
	s_add_u32 s0, s71, 0x800
	v_lshlrev_b32_e32 v180, 1, v13
	v_add_u32_e32 v13, s35, v17
	v_lshl_add_u64 v[6:7], v[6:7], 0, v[8:9]
	v_lshl_add_u64 v[4:5], v[4:5], 0, v[8:9]
	s_addc_u32 s1, s94, 0
	v_lshlrev_b32_e32 v16, 1, v13
	global_load_dwordx4 v[32:35], v[6:7], off nt
	global_load_dwordx4 v[8:11], v[4:5], off nt
	global_load_dwordx4 v[28:31], v[6:7], off offset:64 nt
	s_nop 0
	global_load_dwordx4 v[4:7], v[4:5], off offset:64 nt
	v_xor_b32_e32 v16, v16, v15
	v_and_b32_e32 v18, 1, v15
	s_waitcnt lgkmcnt(0)
	s_barrier
	s_add_u32 s6, s0, 0x70000
	v_and_or_b32 v16, v16, 14, v18
	v_mul_lo_u32 v13, v13, s36
	s_addc_u32 s7, s1, 0
	s_mov_b32 m0, s90
	v_lshl_or_b32 v184, v16, 4, v13
	global_load_lds_dwordx4 v180, s[4:5]
	s_mov_b32 m0, s43
	v_lshlrev_b32_e32 v16, 2, v17
	global_load_lds_dwordx4 v184, s[0:1]
	s_add_u32 s0, s9, 0xe0400
	s_addc_u32 s1, s81, 0
	s_add_u32 s4, s71, 0xe0800
	v_bfe_u32 v13, v15, 2, 2
	v_lshlrev_b32_e32 v19, 3, v15
	s_mov_b32 m0, s38
	s_addc_u32 s5, s94, 0
	v_or_b32_e32 v18, v16, v13
	v_and_b32_e32 v19, 24, v19
	global_load_lds_dwordx4 v184, s[6:7]
	s_add_u32 s6, s4, 0x70000
	v_lshlrev_b32_e32 v13, 5, v18
	v_lshl_or_b32 v18, v18, 8, v19
	v_bitop3_b32 v19, v17, v15, 7 bitop3:0x78
	v_add_u32_e32 v17, 4, v17
	s_addc_u32 s7, s5, 0
	s_add_i32 s8, s8, s29
	v_bitop3_b32 v15, v17, v15, 7 bitop3:0x78
	v_add_u32_e32 v188, 0x4000, v18
	v_or_b32_e32 v18, s8, v14
	v_lshlrev_b32_e32 v205, 4, v15
	v_lshl_add_u32 v15, s83, 6, v16
	v_cvt_f32_u32_e32 v18, v18
	v_cvt_f32_i32_e32 v17, v15
	s_mov_b32 m0, s39
	v_writelane_b32 v255, s9, 8
	v_sub_f32_e32 v17, v17, v18
	global_load_lds_dwordx4 v180, s[0:1]
	v_cmp_lt_f32_e64 s[0:1], 0, v17
	v_mul_f32_e32 v17, v17, v12
	v_exp_f32_e32 v189, v17
	v_or_b32_e32 v17, 1, v15
	v_cvt_f32_i32_e32 v17, v17
	s_mov_b32 m0, s40
	s_add_i32 s14, s14, s29
	global_load_lds_dwordx4 v184, s[4:5]
	v_sub_f32_e32 v17, v17, v18
	v_cmp_lt_f32_e64 s[68:69], 0, v17
	v_mul_f32_e32 v17, v17, v12
	v_exp_f32_e32 v190, v17
	v_or_b32_e32 v17, 2, v15
	v_cvt_f32_i32_e32 v17, v17
	s_mov_b32 m0, s41
	v_lshlrev_b32_e32 v201, 7, v14
	global_load_lds_dwordx4 v184, s[6:7]
	v_sub_f32_e32 v17, v17, v18
	v_cmp_lt_f32_e64 s[4:5], 0, v17
	v_mul_f32_e32 v17, v17, v12
	v_exp_f32_e32 v191, v17
	v_or_b32_e32 v17, 3, v15
	v_cvt_f32_i32_e32 v17, v17
	v_or_b32_e32 v14, s14, v14
	v_cvt_f32_u32_e32 v14, v14
	s_waitcnt vmcnt(3) lgkmcnt(0)
	s_barrier
; __device__ __forceinline__ void ret_pair(LAS unsigned char* lds, const bf16_t* Z, bf16_t* MIX, int b, int h, int tA, int tB, const float* gain, int wid) {
;     ...
;     f32x4 OA[8], OB[8];
; #pragma unroll
;     for (int eb = 0; eb < 8; ++eb) { OA[eb] = (f32x4){0.f, 0.f, 0.f, 0.f}; OB[eb] = OA[eb]; }
;     ...
;     const float iqA = (float)(128 * tA + 16 * wid + q16), iqB = (float)(128 * tB + 16 * wid + q16);
	v_sub_f32_e32 v17, v17, v18
	v_cmp_lt_f32_e64 s[6:7], 0, v17
	v_mul_f32_e32 v17, v17, v12
	v_exp_f32_e32 v192, v17
	v_add_u32_e32 v17, 16, v15
	v_cvt_f32_i32_e32 v17, v17
	v_mov_b32_e32 v48, v181
	v_mov_b32_e32 v49, v181
	v_mov_b32_e32 v50, v181
	v_sub_f32_e32 v17, v17, v18
	v_cmp_lt_f32_e64 s[8:9], 0, v17
	v_mul_f32_e32 v17, v17, v12
	v_exp_f32_e32 v193, v17
	v_add_u32_e32 v17, 17, v15
	v_cvt_f32_i32_e32 v17, v17
	v_mov_b32_e32 v51, v181
	v_and_b32_e32 v187, 0xe0, v13
	v_lshlrev_b32_e32 v204, 4, v19
	v_sub_f32_e32 v17, v17, v18
	v_cmp_lt_f32_e64 s[10:11], 0, v17
	v_mul_f32_e32 v17, v17, v12
	v_exp_f32_e32 v194, v17
	v_add_u32_e32 v17, 18, v15
	v_cvt_f32_i32_e32 v17, v17
	v_bitop3_b32 v207, v13, 32, v186 bitop3:0x6c
	v_bitop3_b32 v226, v13, 64, v186 bitop3:0x6c
	v_bitop3_b32 v224, v13, s73, v186 bitop3:0x6c
	v_sub_f32_e32 v17, v17, v18
	v_cmp_lt_f32_e64 s[12:13], 0, v17
	v_mul_f32_e32 v17, v17, v12
	v_exp_f32_e32 v195, v17
	v_add_u32_e32 v17, 19, v15
	v_cvt_f32_i32_e32 v17, v17
	v_bitop3_b32 v221, v13, s74, v186 bitop3:0x6c
	v_bitop3_b32 v220, v13, s75, v186 bitop3:0x6c
	v_bitop3_b32 v217, v13, s79, v186 bitop3:0x6c
	v_sub_f32_e32 v17, v17, v18
	v_cmp_lt_f32_e64 s[14:15], 0, v17
	v_mul_f32_e32 v17, v17, v12
	v_exp_f32_e32 v196, v17
	v_add_u32_e32 v17, 32, v15
	v_cvt_f32_i32_e32 v17, v17
	v_bitop3_b32 v216, v13, s67, v13 bitop3:0xc
	v_mov_b64_e32 v[44:45], v[48:49]
	v_mov_b64_e32 v[40:41], v[48:49]
	v_sub_f32_e32 v17, v17, v18
	v_cmp_lt_f32_e64 s[16:17], 0, v17
	v_mul_f32_e32 v17, v17, v12
	v_exp_f32_e32 v197, v17
	v_add_u32_e32 v17, 33, v15
	v_cvt_f32_i32_e32 v17, v17
	v_mov_b64_e32 v[36:37], v[48:49]
	v_mov_b64_e32 v[24:25], v[48:49]
	v_mov_b64_e32 v[20:21], v[48:49]
	v_sub_f32_e32 v17, v17, v18
	v_cmp_lt_f32_e64 s[18:19], 0, v17
	v_mul_f32_e32 v17, v17, v12
	v_exp_f32_e32 v198, v17
	v_add_u32_e32 v17, 34, v15
	v_cvt_f32_i32_e32 v17, v17
	v_mov_b64_e32 v[82:83], v[50:51]
	v_mov_b64_e32 v[78:79], v[50:51]
	v_mov_b64_e32 v[74:75], v[50:51]
	v_sub_f32_e32 v17, v17, v18
	v_cmp_lt_f32_e64 s[20:21], 0, v17
	v_mul_f32_e32 v17, v17, v12
	v_exp_f32_e32 v199, v17
	v_add_u32_e32 v17, 35, v15
	v_cvt_f32_i32_e32 v17, v17
	v_mov_b64_e32 v[70:71], v[50:51]
	v_mov_b64_e32 v[66:67], v[50:51]
	v_mov_b64_e32 v[62:63], v[50:51]
	v_sub_f32_e32 v17, v17, v18
	v_cmp_lt_f32_e64 s[22:23], 0, v17
	v_mul_f32_e32 v17, v17, v12
	v_exp_f32_e32 v200, v17
	v_add_u32_e32 v17, 48, v15
	v_cvt_f32_i32_e32 v17, v17
	v_mov_b64_e32 v[58:59], v[50:51]
	v_mov_b64_e32 v[54:55], v[50:51]
	v_mov_b32_e32 v185, v181
	v_sub_f32_e32 v17, v17, v18
	v_cmp_lt_f32_e64 s[24:25], 0, v17
	v_mul_f32_e32 v17, v17, v12
	v_exp_f32_e32 v203, v17
	v_add_u32_e32 v17, 49, v15
	v_cvt_f32_i32_e32 v17, v17
	s_mov_b32 s66, 0
	v_mov_b64_e32 v[46:47], v[50:51]
	v_mov_b64_e32 v[42:43], v[50:51]
	v_sub_f32_e32 v17, v17, v18
	v_cmp_lt_f32_e64 s[26:27], 0, v17
	v_mul_f32_e32 v17, v17, v12
	v_exp_f32_e32 v206, v17
	v_add_u32_e32 v17, 50, v15
	v_add_u32_e32 v15, 51, v15
	v_cvt_f32_i32_e32 v15, v15
	v_cvt_f32_i32_e32 v17, v17
	v_mov_b64_e32 v[38:39], v[50:51]
	v_mov_b64_e32 v[26:27], v[50:51]
	v_sub_f32_e32 v15, v15, v18
	v_cmp_lt_f32_e64 s[34:35], 0, v15
	v_mul_f32_e32 v15, v15, v12
	v_exp_f32_e32 v211, v15
	v_lshl_add_u32 v15, s91, 6, v16
	v_cvt_f32_i32_e32 v16, v15
	v_sub_f32_e32 v17, v17, v18
	v_cmp_lt_f32_e64 s[28:29], 0, v17
	v_mul_f32_e32 v17, v17, v12
	v_sub_f32_e32 v16, v16, v14
	v_cmp_lt_f32_e64 s[30:31], 0, v16
	v_mul_f32_e32 v16, v16, v12
	v_exp_f32_e32 v208, v16
	v_or_b32_e32 v16, 1, v15
	v_cvt_f32_i32_e32 v16, v16
	v_exp_f32_e32 v209, v17
	v_mov_b64_e32 v[22:23], v[50:51]
	v_mov_b64_e32 v[80:81], v[48:49]
	v_sub_f32_e32 v16, v16, v14
	v_cmp_lt_f32_e64 s[36:37], 0, v16
	v_mul_f32_e32 v16, v16, v12
	v_exp_f32_e32 v210, v16
	v_or_b32_e32 v16, 2, v15
	v_cvt_f32_i32_e32 v16, v16
	v_mov_b64_e32 v[76:77], v[48:49]
	v_mov_b64_e32 v[72:73], v[48:49]
	v_mov_b64_e32 v[68:69], v[48:49]
	v_sub_f32_e32 v16, v16, v14
	v_cmp_lt_f32_e64 s[38:39], 0, v16
	v_mul_f32_e32 v16, v16, v12
	v_exp_f32_e32 v252, v16
	v_or_b32_e32 v16, 3, v15
	v_cvt_f32_i32_e32 v16, v16
	v_mov_b64_e32 v[64:65], v[48:49]
	v_mov_b64_e32 v[60:61], v[48:49]
	v_mov_b64_e32 v[56:57], v[48:49]
	v_sub_f32_e32 v16, v16, v14
	v_cmp_lt_f32_e64 s[40:41], 0, v16
	v_mul_f32_e32 v16, v16, v12
	v_exp_f32_e32 v253, v16
	v_add_u32_e32 v16, 16, v15
	v_cvt_f32_i32_e32 v16, v16
	v_mov_b64_e32 v[52:53], v[48:49]
	s_mov_b32 s73, 0
	v_sub_f32_e32 v16, v16, v14
	v_cmp_lt_f32_e64 s[42:43], 0, v16
	v_mul_f32_e32 v16, v16, v12
	v_exp_f32_e32 v202, v16
	v_add_u32_e32 v16, 17, v15
	v_cvt_f32_i32_e32 v16, v16
	v_sub_f32_e32 v16, v16, v14
	v_cmp_lt_f32_e64 s[44:45], 0, v16
	v_mul_f32_e32 v16, v16, v12
	v_exp_f32_e32 v182, v16
	v_add_u32_e32 v16, 18, v15
	v_cvt_f32_i32_e32 v16, v16
	v_sub_f32_e32 v16, v16, v14
	v_cmp_lt_f32_e64 s[46:47], 0, v16
	v_mul_f32_e32 v16, v16, v12
	v_exp_f32_e32 v218, v16
	v_add_u32_e32 v16, 19, v15
	v_cvt_f32_i32_e32 v16, v16
	v_sub_f32_e32 v16, v16, v14
	v_cmp_lt_f32_e64 s[48:49], 0, v16
	v_mul_f32_e32 v16, v16, v12
	v_exp_f32_e32 v219, v16
	v_add_u32_e32 v16, 32, v15
	v_cvt_f32_i32_e32 v16, v16
	v_sub_f32_e32 v16, v16, v14
	v_cmp_lt_f32_e64 s[50:51], 0, v16
	v_mul_f32_e32 v16, v16, v12
	v_exp_f32_e32 v222, v16
	v_add_u32_e32 v16, 33, v15
	v_cvt_f32_i32_e32 v16, v16
	v_sub_f32_e32 v16, v16, v14
	v_cmp_lt_f32_e64 s[52:53], 0, v16
	v_mul_f32_e32 v16, v16, v12
	v_exp_f32_e32 v223, v16
	v_add_u32_e32 v16, 34, v15
	v_cvt_f32_i32_e32 v16, v16
	v_sub_f32_e32 v16, v16, v14
	v_cmp_lt_f32_e64 s[54:55], 0, v16
	v_mul_f32_e32 v16, v16, v12
	v_exp_f32_e32 v225, v16
	v_add_u32_e32 v16, 35, v15
	v_cvt_f32_i32_e32 v16, v16
	v_sub_f32_e32 v16, v16, v14
	v_cmp_lt_f32_e64 s[56:57], 0, v16
	v_mul_f32_e32 v16, v16, v12
	v_exp_f32_e32 v227, v16
	v_add_u32_e32 v16, 48, v15
	v_cvt_f32_i32_e32 v16, v16
	v_sub_f32_e32 v16, v16, v14
	v_cmp_lt_f32_e64 s[58:59], 0, v16
	v_mul_f32_e32 v16, v16, v12
	v_exp_f32_e32 v228, v16
	v_add_u32_e32 v16, 49, v15
	v_cvt_f32_i32_e32 v16, v16
	v_sub_f32_e32 v16, v16, v14
	v_cmp_lt_f32_e64 s[60:61], 0, v16
	v_mul_f32_e32 v16, v16, v12
	v_exp_f32_e32 v229, v16
	v_add_u32_e32 v16, 50, v15
	v_add_u32_e32 v15, 51, v15
	v_cvt_f32_i32_e32 v16, v16
	v_cvt_f32_i32_e32 v15, v15
	v_sub_f32_e32 v16, v16, v14
	v_sub_f32_e32 v14, v15, v14
	v_cmp_lt_f32_e64 s[62:63], 0, v16
	v_mul_f32_e32 v16, v16, v12
	v_mul_f32_e32 v12, v14, v12
	v_exp_f32_e32 v230, v16
	v_exp_f32_e32 v231, v12
	v_cmp_lt_f32_e64 s[64:65], 0, v14
	v_mov_b64_e32 v[16:17], v[48:49]
	v_mov_b64_e32 v[12:13], v[48:49]
	v_mov_b64_e32 v[18:19], v[50:51]
	v_mov_b64_e32 v[14:15], v[50:51]
	s_waitcnt vmcnt(0)

; __device__ __forceinline__ int lane_id() { return (int)__builtin_amdgcn_mbcnt_hi(~0u, __builtin_amdgcn_mbcnt_lo(~0u, 0u)); }
; __device__ __forceinline__ void ret_pair(LAS unsigned char* lds, const bf16_t* Z, bf16_t* MIX, int b, int h, int tA, int tB, const float* gain, int wid) {
;     ...
;     int lf = lane_id(); asm volatile("" : "+v"(lf)); const int q16f = lf & 15, quadf = (lf >> 4) & 3;
; #pragma unroll
;     for (int which = 0; which < 2; ++which) {
;         f32x4 (&O)[8] = which ? OB : OA;
;         float ss = 0.f;
; #pragma unroll
;         for (int eb = 0; eb < 8; ++eb)
; #pragma unroll
;             for (int i = 0; i < 4; ++i) ss += O[eb][i] * O[eb][i];
;         ss = quad_sum(ss);
;         const float r = rsqrtf(ss * (1.0f / 128.0f) + EPS);
;         const int row = (which ? rowB0 : rowA0) + q16f;
;         const bf16_t* gp = Z + (size_t)row * DIN + gcol + 4 * quadf;
;         bf16_t* op = MIX + (size_t)row * DM + 128 * h + 4 * quadf;
; #pragma unroll
;         for (int eb = 0; eb < 8; ++eb) {
;             const u32x2 gw = *(const u32x2*)(gp + 16 * eb);
;             const f32x4 gn = *(const f32x4*)(gain + 16 * eb + 4 * quadf);
.LBB0_640:
	s_lshl_b32 s0, s80, 2
	v_readlane_b32 s1, v254, 24
	s_add_u32 s0, s1, s0
	v_readlane_b32 s1, v254, 23
	v_readlane_b32 s2, v255, 3
	s_waitcnt lgkmcnt(0)
	v_mov_b32_e32 v4, v183
	s_addc_u32 s1, s1, 0
	s_add_i32 s4, s2, 1
	s_add_u32 s2, s30, s86
	v_and_b32_e32 v93, 15, v4
	v_lshrrev_b32_e32 v4, 2, v4
	s_addc_u32 s3, s31, 0
	v_and_b32_e32 v4, 12, v4
	v_lshlrev_b32_e32 v180, 1, v4
	v_lshlrev_b32_e32 v4, 2, v4
	v_mov_b32_e32 v5, v181
	v_or_b32_e32 v32, s5, v93
	v_mov_b64_e32 v[6:7], s[2:3]
	v_lshl_add_u64 v[4:5], s[0:1], 0, v[4:5]
	v_readlane_b32 s3, v255, 7
	s_mov_b64 s[6:7], 0x1000
	v_mad_i64_i32 v[8:9], vcc, v32, s36, v[6:7]
	v_mov_b32_e32 v29, v181
	v_or_b32_e32 v30, s3, v93
	v_lshl_add_u64 v[10:11], v[8:9], 0, v[180:181]
	v_mad_i64_i32 v[6:7], vcc, v30, s36, v[6:7]
	v_lshl_add_u64 v[10:11], v[10:11], 0, s[6:7]
	v_lshl_add_u64 v[6:7], v[6:7], 0, v[180:181]
	s_add_u32 s0, s88, s86
	s_addc_u32 s1, s89, 0
	v_lshl_add_u64 v[6:7], v[6:7], 0, s[6:7]
	global_load_dwordx4 v[96:99], v[4:5], off
	global_load_dwordx2 v[134:135], v[10:11], off
	global_load_dwordx2 v[150:151], v[6:7], off
	global_load_dwordx4 v[100:103], v[4:5], off offset:64
	global_load_dwordx2 v[136:137], v[10:11], off offset:32
	global_load_dwordx2 v[152:153], v[6:7], off offset:32
	global_load_dwordx4 v[104:107], v[4:5], off offset:128
	global_load_dwordx2 v[138:139], v[10:11], off offset:64
	global_load_dwordx2 v[154:155], v[6:7], off offset:64
	global_load_dwordx4 v[108:111], v[4:5], off offset:192
	global_load_dwordx2 v[140:141], v[10:11], off offset:96
	global_load_dwordx2 v[156:157], v[6:7], off offset:96
	global_load_dwordx4 v[112:115], v[4:5], off offset:256
	global_load_dwordx2 v[142:143], v[10:11], off offset:128
	global_load_dwordx2 v[158:159], v[6:7], off offset:128
	global_load_dwordx4 v[116:119], v[4:5], off offset:320
	global_load_dwordx2 v[144:145], v[10:11], off offset:160
	global_load_dwordx2 v[160:161], v[6:7], off offset:160
	global_load_dwordx4 v[120:123], v[4:5], off offset:384
	global_load_dwordx2 v[146:147], v[10:11], off offset:192
	global_load_dwordx2 v[162:163], v[6:7], off offset:192
	global_load_dwordx4 v[124:127], v[4:5], off offset:448
	global_load_dwordx2 v[148:149], v[10:11], off offset:224
	global_load_dwordx2 v[164:165], v[6:7], off offset:224
	v_lshl_add_u64 v[8:9], s[0:1], 0, v[180:181]
	v_mov_b32_e32 v28, v32
	v_mov_b32_e32 v31, v181
	v_lshlrev_b64 v[28:29], 12, v[28:29]
	v_lshlrev_b64 v[30:31], 12, v[30:31]
	v_lshl_add_u64 v[166:167], v[8:9], 0, v[28:29]
	v_lshl_add_u64 v[168:169], v[8:9], 0, v[30:31]
	v_mul_f32_e32 v33, v81, v81
	v_fmac_f32_e32 v33, v80, v80
	v_fmac_f32_e32 v33, v82, v82
	v_fmac_f32_e32 v33, v83, v83
	v_fmac_f32_e32 v33, v76, v76
	v_fmac_f32_e32 v33, v77, v77
	v_fmac_f32_e32 v33, v78, v78
	v_fmac_f32_e32 v33, v79, v79
	v_fmac_f32_e32 v33, v72, v72
	v_fmac_f32_e32 v33, v73, v73
	v_fmac_f32_e32 v33, v74, v74
	v_fmac_f32_e32 v33, v75, v75
	v_fmac_f32_e32 v33, v68, v68
	v_fmac_f32_e32 v33, v69, v69
	v_fmac_f32_e32 v33, v70, v70
	v_fmac_f32_e32 v33, v71, v71
	v_fmac_f32_e32 v33, v64, v64
	v_fmac_f32_e32 v33, v65, v65
	v_fmac_f32_e32 v33, v66, v66
	v_fmac_f32_e32 v33, v67, v67
	v_fmac_f32_e32 v33, v60, v60
	v_fmac_f32_e32 v33, v61, v61
	v_fmac_f32_e32 v33, v62, v62
	v_fmac_f32_e32 v33, v63, v63
	v_pk_mul_f32 v[84:85], v[56:57], v[56:57]
	v_pk_mul_f32 v[8:9], v[58:59], v[58:59]
	v_add_f32_e32 v33, v84, v33
	v_add_f32_e32 v33, v85, v33
	v_add_f32_e32 v8, v8, v33
	v_add_f32_e32 v33, v9, v8
	v_pk_mul_f32 v[84:85], v[52:53], v[52:53]
	v_pk_mul_f32 v[8:9], v[54:55], v[54:55]
	v_add_f32_e32 v33, v84, v33
	v_add_f32_e32 v33, v85, v33
	v_add_f32_e32 v8, v8, v33
	v_add_f32_e32 v33, v9, v8
	ds_swizzle_b32 v84, v33 offset:swizzle(SWAP,16)
	v_pk_mul_f32 v[90:91], v[16:17], v[16:17]
	v_pk_mul_f32 v[88:89], v[18:19], v[18:19]
	s_waitcnt lgkmcnt(0)
	v_add_f32_e32 v85, v33, v84
	v_mul_f32_e32 v84, v49, v49
	v_fmac_f32_e32 v84, v48, v48
	v_fmac_f32_e32 v84, v50, v50
	v_fmac_f32_e32 v84, v51, v51
	v_fmac_f32_e32 v84, v44, v44
	v_fmac_f32_e32 v84, v45, v45
	v_fmac_f32_e32 v84, v46, v46
	v_fmac_f32_e32 v84, v47, v47
	v_fmac_f32_e32 v84, v40, v40
	v_fmac_f32_e32 v84, v41, v41
	v_fmac_f32_e32 v84, v42, v42
	v_fmac_f32_e32 v84, v43, v43
	v_fmac_f32_e32 v84, v36, v36
	v_fmac_f32_e32 v84, v37, v37
	v_fmac_f32_e32 v84, v38, v38
	v_fmac_f32_e32 v84, v39, v39
	v_fmac_f32_e32 v84, v24, v24
	v_fmac_f32_e32 v84, v25, v25
	v_fmac_f32_e32 v84, v26, v26
	v_fmac_f32_e32 v84, v27, v27
	v_fmac_f32_e32 v84, v20, v20
	v_fmac_f32_e32 v84, v21, v21
	v_fmac_f32_e32 v84, v22, v22
	v_fmac_f32_e32 v84, v23, v23
	v_add_f32_e32 v84, v90, v84
	v_add_f32_e32 v84, v91, v84
	v_add_f32_e32 v84, v88, v84
	v_add_f32_e32 v84, v89, v84
	v_pk_mul_f32 v[90:91], v[12:13], v[12:13]
	v_pk_mul_f32 v[88:89], v[14:15], v[14:15]
	v_add_f32_e32 v84, v90, v84
	v_add_f32_e32 v84, v91, v84
	v_add_f32_e32 v84, v88, v84
	v_add_f32_e32 v84, v89, v84
	ds_swizzle_b32 v86, v84 offset:swizzle(SWAP,16)
	v_mov_b32_e32 v87, v85
	s_nop 1
	v_permlane32_swap_b32_e32 v85, v87
	s_waitcnt lgkmcnt(0)
	v_add_f32_e32 v84, v84, v86
	v_mov_b32_e32 v86, v84
	s_nop 1
	v_permlane32_swap_b32_e32 v84, v86
	v_pk_add_f32 v[84:85], v[84:85], v[86:87]
	s_brev_b32 s0, 60
	v_mov_b32_e32 v34, 0x358637bd
	v_pk_fma_f32 v[84:85], v[84:85], s[0:1], v[34:35] op_sel_hi:[1,0,0]
	s_mov_b32 s2, 0x800000
	v_mul_f32_e32 v34, 0x4b800000, v85
	v_cmp_gt_f32_e32 vcc, s2, v85
	v_mul_f32_e32 v35, 0x4b800000, v84
	v_cmp_gt_f32_e64 s[0:1], s2, v84
	v_cndmask_b32_e32 v34, v85, v34, vcc
	v_rsq_f32_e32 v85, v34
	v_cndmask_b32_e64 v35, v84, v35, s[0:1]
	v_rsq_f32_e32 v84, v35
	v_mul_f32_e32 v92, 0x45800000, v85
	v_cndmask_b32_e32 v92, v85, v92, vcc
	v_mul_f32_e32 v94, 0x45800000, v84
	v_cndmask_b32_e64 v94, v84, v94, s[0:1]
	s_mov_b32 s87, s27
	s_mov_b32 m0, s90
	s_mov_b32 s42, 0x800000
	s_mov_b32 s5, 0
	s_waitcnt vmcnt(0)
; __device__ __forceinline__ unsigned cvtpk(float lo, float hi) { f32x2 v = {lo, hi}; bf16x2_t b = __builtin_convertvector(v, bf16x2_t); return __builtin_bit_cast(unsigned, b); }
; __device__ __forceinline__ float bflo(unsigned u) { return __uint_as_float(u << 16); }
; __device__ __forceinline__ float bfhi(unsigned u) { return __uint_as_float(u & 0xffff0000u); }
; __device__ __forceinline__ void ret_pair(LAS unsigned char* lds, const bf16_t* Z, bf16_t* MIX, int b, int h, int tA, int tB, const float* gain, int wid) {
;     ...
; #pragma unroll
;         for (int eb = 0; eb < 8; ++eb) {
;             const u32x2 gw = *(const u32x2*)(gp + 16 * eb);
;             const f32x4 gn = *(const f32x4*)(gain + 16 * eb + 4 * quadf);
;             u32x2 w; w.x = cvtpk(O[eb][0] * r * gn.x * bflo(gw.x), O[eb][1] * r * gn.y * bfhi(gw.x));
;             w.y = cvtpk(O[eb][2] * r * gn.z * bflo(gw.y), O[eb][3] * r * gn.w * bfhi(gw.y));
;             *(u32x2*)(op + 16 * eb) = w;
	v_pk_mul_f32 v[80:81], v[80:81], v[92:93] op_sel_hi:[1,0]
	v_pk_mul_f32 v[82:83], v[82:83], v[92:93] op_sel_hi:[1,0]
	v_lshlrev_b32_e32 v28, 16, v134
	v_and_b32_e32 v29, 0xffff0000, v134
	v_lshlrev_b32_e32 v30, 16, v135
	v_and_b32_e32 v31, 0xffff0000, v135
	v_pk_mul_f32 v[80:81], v[96:97], v[80:81]
	v_pk_mul_f32 v[82:83], v[98:99], v[82:83]
	v_pk_mul_f32 v[80:81], v[80:81], v[28:29]
	v_pk_mul_f32 v[82:83], v[82:83], v[30:31]
	v_cvt_pk_bf16_f32 v80, v80, v81
	v_cvt_pk_bf16_f32 v81, v82, v83
	global_store_dwordx2 v[166:167], v[80:81], off
	v_pk_mul_f32 v[48:49], v[48:49], v[94:95] op_sel_hi:[1,0]
	v_pk_mul_f32 v[50:51], v[50:51], v[94:95] op_sel_hi:[1,0]
	v_lshlrev_b32_e32 v170, 16, v150
	v_and_b32_e32 v171, 0xffff0000, v150
	v_lshlrev_b32_e32 v172, 16, v151
	v_and_b32_e32 v173, 0xffff0000, v151
	v_pk_mul_f32 v[48:49], v[96:97], v[48:49]
	v_pk_mul_f32 v[50:51], v[98:99], v[50:51]
	v_pk_mul_f32 v[48:49], v[48:49], v[170:171]
	v_pk_mul_f32 v[50:51], v[50:51], v[172:173]
	v_cvt_pk_bf16_f32 v48, v48, v49
	v_cvt_pk_bf16_f32 v49, v50, v51
	global_store_dwordx2 v[168:169], v[48:49], off
	v_pk_mul_f32 v[76:77], v[76:77], v[92:93] op_sel_hi:[1,0]
	v_pk_mul_f32 v[78:79], v[78:79], v[92:93] op_sel_hi:[1,0]
	v_lshlrev_b32_e32 v28, 16, v136
	v_and_b32_e32 v29, 0xffff0000, v136
	v_lshlrev_b32_e32 v30, 16, v137
	v_and_b32_e32 v31, 0xffff0000, v137
	v_pk_mul_f32 v[76:77], v[100:101], v[76:77]
	v_pk_mul_f32 v[78:79], v[102:103], v[78:79]
	v_pk_mul_f32 v[76:77], v[76:77], v[28:29]
	v_pk_mul_f32 v[78:79], v[78:79], v[30:31]
	v_cvt_pk_bf16_f32 v76, v76, v77
	v_cvt_pk_bf16_f32 v77, v78, v79
	global_store_dwordx2 v[166:167], v[76:77], off offset:32
	v_pk_mul_f32 v[44:45], v[44:45], v[94:95] op_sel_hi:[1,0]
	v_pk_mul_f32 v[46:47], v[46:47], v[94:95] op_sel_hi:[1,0]
	v_lshlrev_b32_e32 v170, 16, v152
	v_and_b32_e32 v171, 0xffff0000, v152
	v_lshlrev_b32_e32 v172, 16, v153
	v_and_b32_e32 v173, 0xffff0000, v153
	v_pk_mul_f32 v[44:45], v[100:101], v[44:45]
	v_pk_mul_f32 v[46:47], v[102:103], v[46:47]
	v_pk_mul_f32 v[44:45], v[44:45], v[170:171]
	v_pk_mul_f32 v[46:47], v[46:47], v[172:173]
	v_cvt_pk_bf16_f32 v44, v44, v45
	v_cvt_pk_bf16_f32 v45, v46, v47
	global_store_dwordx2 v[168:169], v[44:45], off offset:32
	v_pk_mul_f32 v[72:73], v[72:73], v[92:93] op_sel_hi:[1,0]
	v_pk_mul_f32 v[74:75], v[74:75], v[92:93] op_sel_hi:[1,0]
	v_lshlrev_b32_e32 v28, 16, v138
	v_and_b32_e32 v29, 0xffff0000, v138
	v_lshlrev_b32_e32 v30, 16, v139
	v_and_b32_e32 v31, 0xffff0000, v139
	v_pk_mul_f32 v[72:73], v[104:105], v[72:73]
	v_pk_mul_f32 v[74:75], v[106:107], v[74:75]
	v_pk_mul_f32 v[72:73], v[72:73], v[28:29]
	v_pk_mul_f32 v[74:75], v[74:75], v[30:31]
	v_cvt_pk_bf16_f32 v72, v72, v73
	v_cvt_pk_bf16_f32 v73, v74, v75
	global_store_dwordx2 v[166:167], v[72:73], off offset:64
	v_pk_mul_f32 v[40:41], v[40:41], v[94:95] op_sel_hi:[1,0]
	v_pk_mul_f32 v[42:43], v[42:43], v[94:95] op_sel_hi:[1,0]
	v_lshlrev_b32_e32 v170, 16, v154
	v_and_b32_e32 v171, 0xffff0000, v154
	v_lshlrev_b32_e32 v172, 16, v155
	v_and_b32_e32 v173, 0xffff0000, v155
	v_pk_mul_f32 v[40:41], v[104:105], v[40:41]
	v_pk_mul_f32 v[42:43], v[106:107], v[42:43]
	v_pk_mul_f32 v[40:41], v[40:41], v[170:171]
	v_pk_mul_f32 v[42:43], v[42:43], v[172:173]
	v_cvt_pk_bf16_f32 v40, v40, v41
	v_cvt_pk_bf16_f32 v41, v42, v43
	global_store_dwordx2 v[168:169], v[40:41], off offset:64
	v_pk_mul_f32 v[68:69], v[68:69], v[92:93] op_sel_hi:[1,0]
	v_pk_mul_f32 v[70:71], v[70:71], v[92:93] op_sel_hi:[1,0]
	v_lshlrev_b32_e32 v28, 16, v140
	v_and_b32_e32 v29, 0xffff0000, v140
	v_lshlrev_b32_e32 v30, 16, v141
	v_and_b32_e32 v31, 0xffff0000, v141
	v_pk_mul_f32 v[68:69], v[108:109], v[68:69]
	v_pk_mul_f32 v[70:71], v[110:111], v[70:71]
	v_pk_mul_f32 v[68:69], v[68:69], v[28:29]
	v_pk_mul_f32 v[70:71], v[70:71], v[30:31]
	v_cvt_pk_bf16_f32 v68, v68, v69
	v_cvt_pk_bf16_f32 v69, v70, v71
	global_store_dwordx2 v[166:167], v[68:69], off offset:96
	v_pk_mul_f32 v[36:37], v[36:37], v[94:95] op_sel_hi:[1,0]
	v_pk_mul_f32 v[38:39], v[38:39], v[94:95] op_sel_hi:[1,0]
	v_lshlrev_b32_e32 v170, 16, v156
	v_and_b32_e32 v171, 0xffff0000, v156
	v_lshlrev_b32_e32 v172, 16, v157
	v_and_b32_e32 v173, 0xffff0000, v157
	v_pk_mul_f32 v[36:37], v[108:109], v[36:37]
	v_pk_mul_f32 v[38:39], v[110:111], v[38:39]
	v_pk_mul_f32 v[36:37], v[36:37], v[170:171]
	v_pk_mul_f32 v[38:39], v[38:39], v[172:173]
	v_cvt_pk_bf16_f32 v36, v36, v37
	v_cvt_pk_bf16_f32 v37, v38, v39
	global_store_dwordx2 v[168:169], v[36:37], off offset:96
	v_pk_mul_f32 v[64:65], v[64:65], v[92:93] op_sel_hi:[1,0]
	v_pk_mul_f32 v[66:67], v[66:67], v[92:93] op_sel_hi:[1,0]
	v_lshlrev_b32_e32 v28, 16, v142
	v_and_b32_e32 v29, 0xffff0000, v142
	v_lshlrev_b32_e32 v30, 16, v143
	v_and_b32_e32 v31, 0xffff0000, v143
	v_pk_mul_f32 v[64:65], v[112:113], v[64:65]
	v_pk_mul_f32 v[66:67], v[114:115], v[66:67]
	v_pk_mul_f32 v[64:65], v[64:65], v[28:29]
	v_pk_mul_f32 v[66:67], v[66:67], v[30:31]
	v_cvt_pk_bf16_f32 v64, v64, v65
	v_cvt_pk_bf16_f32 v65, v66, v67
	global_store_dwordx2 v[166:167], v[64:65], off offset:128
	v_pk_mul_f32 v[24:25], v[24:25], v[94:95] op_sel_hi:[1,0]
	v_pk_mul_f32 v[26:27], v[26:27], v[94:95] op_sel_hi:[1,0]
	v_lshlrev_b32_e32 v170, 16, v158
	v_and_b32_e32 v171, 0xffff0000, v158
	v_lshlrev_b32_e32 v172, 16, v159
	v_and_b32_e32 v173, 0xffff0000, v159
	v_pk_mul_f32 v[24:25], v[112:113], v[24:25]
	v_pk_mul_f32 v[26:27], v[114:115], v[26:27]
	v_pk_mul_f32 v[24:25], v[24:25], v[170:171]
	v_pk_mul_f32 v[26:27], v[26:27], v[172:173]
	v_cvt_pk_bf16_f32 v24, v24, v25
	v_cvt_pk_bf16_f32 v25, v26, v27
	global_store_dwordx2 v[168:169], v[24:25], off offset:128
	v_pk_mul_f32 v[60:61], v[60:61], v[92:93] op_sel_hi:[1,0]
; #define LAS __attribute__((address_space(3)))
; __device__ __forceinline__ unsigned cvtpk(float lo, float hi) { f32x2 v = {lo, hi}; bf16x2_t b = __builtin_convertvector(v, bf16x2_t); return __builtin_bit_cast(unsigned, b); }
; __device__ __forceinline__ float bflo(unsigned u) { return __uint_as_float(u << 16); }
; __device__ __forceinline__ float bfhi(unsigned u) { return __uint_as_float(u & 0xffff0000u); }
; __device__ __forceinline__ int lane_id() { return (int)__builtin_amdgcn_mbcnt_hi(~0u, __builtin_amdgcn_mbcnt_lo(~0u, 0u)); }
; template <bool DIFF>
; __device__ __forceinline__ void attn_item(LAS unsigned char* lds, const bf16_t* Z, bf16_t* MIX, int b, int h, int t, float lam, float shift, const float* gain, int tid, int wid, int lane) {
;     constexpr int NC = DIFF ? 2 : 1;
;     lane = lane_id(); asm volatile("" : "+v"(lane)); tid = wid * 64 + lane;
;     const int q16 = lane & 15, quad = lane >> 4;
;     const int row0 = b * SEQ + 128 * t + 16 * wid;
;     const int cq = 2 * t + (wid >> 2), nkt = 2 * t + 2;
;     const int qcol = DIFF ? (3072 + 128 * h) : (64 * h);
;     const int kcol = DIFF ? (4096 + 128 * h) : (512 + 64 * h);
;     const int vcol = DIFF ? (5120 + 128 * h) : (1024 + 128 * h);
;     const int gcol = DIFF ? (6144 + 128 * h) : (2048 + 128 * h);
;     const float lg = lg2gamma(h);
;     bf16x8 qf[NC][2];
;     { const bf16_t* qrow = Z + (size_t)(row0 + q16) * DIN + qcol;
; #pragma unroll
;       for (int c = 0; c < NC; ++c)
; #pragma unroll
;           for (int ds = 0; ds < 2; ++ds) qf[c][ds] = __builtin_nontemporal_load((const bf16x8*)(qrow + 64 * c + 32 * ds + 8 * quad)); }
; __device__ __forceinline__ void ret_pair(LAS unsigned char* lds, const bf16_t* Z, bf16_t* MIX, int b, int h, int tA, int tB, const float* gain, int wid) {
;     ...
; #pragma unroll
;         for (int eb = 0; eb < 8; ++eb) {
;             const u32x2 gw = *(const u32x2*)(gp + 16 * eb);
;             const f32x4 gn = *(const f32x4*)(gain + 16 * eb + 4 * quadf);
;             u32x2 w; w.x = cvtpk(O[eb][0] * r * gn.x * bflo(gw.x), O[eb][1] * r * gn.y * bfhi(gw.x));
;             w.y = cvtpk(O[eb][2] * r * gn.z * bflo(gw.y), O[eb][3] * r * gn.w * bfhi(gw.y));
;             *(u32x2*)(op + 16 * eb) = w;
	v_pk_mul_f32 v[62:63], v[62:63], v[92:93] op_sel_hi:[1,0]
	v_lshlrev_b32_e32 v28, 16, v144
	v_and_b32_e32 v29, 0xffff0000, v144
	v_lshlrev_b32_e32 v30, 16, v145
	v_and_b32_e32 v31, 0xffff0000, v145
	v_pk_mul_f32 v[60:61], v[116:117], v[60:61]
	v_pk_mul_f32 v[62:63], v[118:119], v[62:63]
	v_pk_mul_f32 v[60:61], v[60:61], v[28:29]
	v_pk_mul_f32 v[62:63], v[62:63], v[30:31]
	v_cvt_pk_bf16_f32 v60, v60, v61
	v_cvt_pk_bf16_f32 v61, v62, v63
	global_store_dwordx2 v[166:167], v[60:61], off offset:160
	v_pk_mul_f32 v[20:21], v[20:21], v[94:95] op_sel_hi:[1,0]
	v_pk_mul_f32 v[22:23], v[22:23], v[94:95] op_sel_hi:[1,0]
	v_lshlrev_b32_e32 v170, 16, v160
	v_and_b32_e32 v171, 0xffff0000, v160
	v_lshlrev_b32_e32 v172, 16, v161
	v_and_b32_e32 v173, 0xffff0000, v161
	v_pk_mul_f32 v[20:21], v[116:117], v[20:21]
	v_pk_mul_f32 v[22:23], v[118:119], v[22:23]
	v_pk_mul_f32 v[20:21], v[20:21], v[170:171]
	v_pk_mul_f32 v[22:23], v[22:23], v[172:173]
	v_cvt_pk_bf16_f32 v20, v20, v21
	v_cvt_pk_bf16_f32 v21, v22, v23
	global_store_dwordx2 v[168:169], v[20:21], off offset:160
	v_pk_mul_f32 v[56:57], v[56:57], v[92:93] op_sel_hi:[1,0]
	v_pk_mul_f32 v[58:59], v[58:59], v[92:93] op_sel_hi:[1,0]
	v_lshlrev_b32_e32 v28, 16, v146
	v_and_b32_e32 v29, 0xffff0000, v146
	v_lshlrev_b32_e32 v30, 16, v147
	v_and_b32_e32 v31, 0xffff0000, v147
	v_pk_mul_f32 v[56:57], v[120:121], v[56:57]
	v_pk_mul_f32 v[58:59], v[122:123], v[58:59]
	v_pk_mul_f32 v[56:57], v[56:57], v[28:29]
	v_pk_mul_f32 v[58:59], v[58:59], v[30:31]
	v_cvt_pk_bf16_f32 v56, v56, v57
	v_cvt_pk_bf16_f32 v57, v58, v59
	global_store_dwordx2 v[166:167], v[56:57], off offset:192
	v_pk_mul_f32 v[16:17], v[16:17], v[94:95] op_sel_hi:[1,0]
	v_pk_mul_f32 v[18:19], v[18:19], v[94:95] op_sel_hi:[1,0]
	v_lshlrev_b32_e32 v170, 16, v162
	v_and_b32_e32 v171, 0xffff0000, v162
	v_lshlrev_b32_e32 v172, 16, v163
	v_and_b32_e32 v173, 0xffff0000, v163
	v_pk_mul_f32 v[16:17], v[120:121], v[16:17]
	v_pk_mul_f32 v[18:19], v[122:123], v[18:19]
	v_pk_mul_f32 v[16:17], v[16:17], v[170:171]
	v_pk_mul_f32 v[18:19], v[18:19], v[172:173]
	v_cvt_pk_bf16_f32 v16, v16, v17
	v_cvt_pk_bf16_f32 v17, v18, v19
	global_store_dwordx2 v[168:169], v[16:17], off offset:192
	v_pk_mul_f32 v[52:53], v[52:53], v[92:93] op_sel_hi:[1,0]
	v_pk_mul_f32 v[54:55], v[54:55], v[92:93] op_sel_hi:[1,0]
	v_lshlrev_b32_e32 v28, 16, v148
	v_and_b32_e32 v29, 0xffff0000, v148
	v_lshlrev_b32_e32 v30, 16, v149
	v_and_b32_e32 v31, 0xffff0000, v149
	v_pk_mul_f32 v[52:53], v[124:125], v[52:53]
	v_pk_mul_f32 v[54:55], v[126:127], v[54:55]
	v_pk_mul_f32 v[52:53], v[52:53], v[28:29]
	v_pk_mul_f32 v[54:55], v[54:55], v[30:31]
	v_cvt_pk_bf16_f32 v52, v52, v53
	v_cvt_pk_bf16_f32 v53, v54, v55
	global_store_dwordx2 v[166:167], v[52:53], off offset:224
	v_pk_mul_f32 v[12:13], v[12:13], v[94:95] op_sel_hi:[1,0]
	v_pk_mul_f32 v[14:15], v[14:15], v[94:95] op_sel_hi:[1,0]
	v_lshlrev_b32_e32 v170, 16, v164
	v_and_b32_e32 v171, 0xffff0000, v164
	v_lshlrev_b32_e32 v172, 16, v165
	v_and_b32_e32 v173, 0xffff0000, v165
	v_pk_mul_f32 v[12:13], v[124:125], v[12:13]
	v_pk_mul_f32 v[14:15], v[126:127], v[14:15]
	v_pk_mul_f32 v[12:13], v[12:13], v[170:171]
	v_pk_mul_f32 v[14:15], v[14:15], v[172:173]
	v_cvt_pk_bf16_f32 v12, v12, v13
	v_cvt_pk_bf16_f32 v13, v14, v15
	global_store_dwordx2 v[168:169], v[12:13], off offset:224
	v_mov_b32_e32 v131, v181
	v_mov_b32_e32 v132, v181
	v_mov_b32_e32 v133, v181
	v_readlane_b32 s6, v254, 52
	v_readlane_b32 s7, v254, 53
	v_mov_b32_e32 v20, v183
	v_mov_b64_e32 v[4:5], s[30:31]
	s_and_b32 s0, s44, 7
	s_sub_i32 s0, 7, s0
	s_lshl_b32 s1, s44, 5
	s_and_b32 s1, s1, 0xfffff800
	s_lshl_b32 s3, s0, 7
	s_or_b32 s3, s3, s1
	s_add_i32 s3, s3, s29
	s_lshl_b32 s82, s0, 1
	s_add_i32 s91, s82, s66
	s_add_i32 s4, s82, 1
	s_nop 0
	v_and_b32_e32 v8, 15, v20
	v_ashrrev_i32_e32 v9, 4, v20
	v_or_b32_e32 v124, s3, v8
	v_ashrrev_i32_e32 v7, 3, v20
	v_lshlrev_b32_e32 v6, 3, v9
	v_mad_i64_i32 v[4:5], s[0:1], v124, s36, v[4:5]
	v_add_u32_e32 v11, s34, v7
	v_xor_b32_e32 v12, v7, v20
	v_ashrrev_i32_e32 v7, 31, v6
	v_lshl_add_u64 v[126:127], v[4:5], 0, s[86:87]
	v_mul_lo_u32 v11, v11, s37
	v_lshlrev_b32_e32 v12, 3, v12
	v_lshl_add_u64 v[4:5], v[6:7], 1, v[126:127]
	v_readlane_b32 s2, v254, 54
	v_add_u32_e32 v13, s35, v9
	v_and_or_b32 v11, v12, 56, v11
	v_lshl_add_u64 v[6:7], v[4:5], 0, s[14:15]
	v_add_co_u32_e32 v4, vcc, s16, v4
	v_readlane_b32 s3, v254, 55
	v_lshlrev_b32_e32 v14, 1, v13
	v_lshlrev_b32_e32 v180, 1, v11
	v_addc_co_u32_e32 v5, vcc, 0, v5, vcc
	global_load_dwordx4 v[76:79], v[6:7], off offset:64 nt
	global_load_dwordx4 v[72:75], v[6:7], off offset:128 nt
	global_load_dwordx4 v[80:83], v[4:5], off offset:2048 nt
	global_load_dwordx4 v[68:71], v[6:7], off offset:192 nt
	s_waitcnt lgkmcnt(0)
	s_barrier
; #define ATT_WAITBAR_ONE() do { if (DIFF) asm volatile("s_waitcnt vmcnt(4) lgkmcnt(0)\n\ts_barrier" ::: "memory"); else asm volatile("s_waitcnt vmcnt(3) lgkmcnt(0)\n\ts_barrier" ::: "memory"); } while (0)
; template <bool DIFF>
; __device__ __forceinline__ void attn_item(LAS unsigned char* lds, const bf16_t* Z, bf16_t* MIX, int b, int h, int t, float lam, float shift, const float* gain, int tid, int wid, int lane) {
;     ...
;     const char* kbase = (const char*)(Z + (size_t)(b * SEQ) * DIN + kcol);
;     const char* vbase = (const char*)(Z + (size_t)(b * SEQ) * DIN + vcol);
;     const unsigned krow = (unsigned)(8 * wid + (lane >> 3));
;     const unsigned kso = (krow * DIN + 8u * ((unsigned)(lane & 7) ^ (krow & 7u))) * 2u;
;     const unsigned vrow = (unsigned)(4 * wid + (lane >> 4));
;     const unsigned vso = (vrow * DIN + 8u * (2u * ((((unsigned)lane & 15u) >> 1) ^ (vrow & 7u)) + ((unsigned)lane & 1u))) * 2u;
;     constexpr int ATT_RING = 32768;
;     ...
;     asm volatile("s_waitcnt lgkmcnt(0)\n\ts_barrier" ::: "memory");
;     ATT_DMA(0, 0); ATT_DMA(1, 1);
;     ATT_WAITBAR_ONE();
;     const unsigned kfo = (unsigned)(q16 * 128), ksw = (unsigned)(q16 & 7);
;     const unsigned vrr = (unsigned)(4 * quad + (q16 >> 2)), vx32 = (vrr & 7u) * 32u, vb0 = 16384u + vrr * 256u + 8u * (unsigned)(q16 & 3);
;     const float iq = (float)(128 * t + 16 * wid + q16);
	s_add_u32 s0, s2, 0x70000
	v_and_b32_e32 v10, 1, v20
	v_xor_b32_e32 v12, v14, v20
	v_lshl_add_u64 v[4:5], s[6:7], 0, v[180:181]
	s_addc_u32 s1, s3, 0
	v_mul_lo_u32 v13, v13, s36
	v_and_or_b32 v10, v12, 14, v10
	v_lshl_add_u64 v[4:5], v[4:5], 0, s[96:97]
	global_load_lds_dwordx4 v180, s[6:7]
	s_mov_b32 m0, s17
	v_lshl_or_b32 v130, v10, 4, v13
	global_load_lds_dwordx4 v[4:5], off
	s_mov_b32 m0, s43
	v_readlane_b32 s6, v254, 58
	global_load_lds_dwordx4 v130, s[2:3]
	v_readlane_b32 s2, v254, 56
	s_mov_b32 m0, s38
	v_readlane_b32 s3, v254, 57
	v_readlane_b32 s7, v254, 59
	global_load_lds_dwordx4 v130, s[0:1]
	s_add_u32 s0, s6, 0x70000
	v_lshl_add_u64 v[4:5], s[2:3], 0, v[180:181]
	s_addc_u32 s1, s7, 0
	s_mov_b32 m0, s39
	v_lshl_add_u64 v[4:5], v[4:5], 0, s[96:97]
	global_load_lds_dwordx4 v180, s[2:3]
	s_mov_b32 m0, s18
	v_lshlrev_b32_e32 v128, 2, v9
	global_load_lds_dwordx4 v[4:5], off
	s_mov_b32 m0, s40
	v_bfe_u32 v4, v20, 2, 2
	global_load_lds_dwordx4 v130, s[6:7]
	s_mov_b32 m0, s41
	v_lshlrev_b32_e32 v6, 3, v20
	global_load_lds_dwordx4 v130, s[0:1]
	v_or_b32_e32 v4, v128, v4
	v_and_b32_e32 v6, 24, v6
	v_lshlrev_b32_e32 v5, 5, v4
	v_lshl_or_b32 v4, v4, 8, v6
	v_add_u32_e32 v143, 0x4000, v4
	v_bitop3_b32 v4, v9, v20, 7 bitop3:0x78
	v_lshlrev_b32_e32 v145, 4, v4
	v_add_u32_e32 v4, 4, v9
	s_waitcnt vmcnt(4) lgkmcnt(0)
	s_barrier
	v_bitop3_b32 v4, v4, v20, 7 bitop3:0x78
	v_mov_b32_e32 v6, v181
	v_mov_b32_e32 v7, v181
	v_lshlrev_b32_e32 v144, 7, v8
	v_and_b32_e32 v142, 0xe0, v5
	v_lshlrev_b32_e32 v146, 4, v4
	v_bitop3_b32 v141, v5, 32, v186 bitop3:0x6c
	v_bitop3_b32 v140, v5, 64, v186 bitop3:0x6c
	v_bitop3_b32 v139, v5, s73, v186 bitop3:0x6c
	v_bitop3_b32 v138, v5, s74, v186 bitop3:0x6c
	v_bitop3_b32 v137, v5, s75, v186 bitop3:0x6c
	v_bitop3_b32 v136, v5, s79, v186 bitop3:0x6c
	v_bitop3_b32 v129, v5, s67, v5 bitop3:0xc
	v_mov_b32_e32 v4, v181
	v_mov_b32_e32 v5, v181
	v_mov_b64_e32 v[14:15], v[6:7]
	v_mov_b64_e32 v[22:23], v[6:7]
	v_mov_b64_e32 v[30:31], v[6:7]
	v_mov_b64_e32 v[38:39], v[6:7]
	v_mov_b64_e32 v[46:47], v[6:7]
	v_mov_b64_e32 v[54:55], v[6:7]
	v_mov_b64_e32 v[62:63], v[6:7]
	v_mov_b64_e32 v[10:11], v[6:7]
	v_mov_b64_e32 v[18:19], v[6:7]
	v_mov_b64_e32 v[26:27], v[6:7]
	v_mov_b64_e32 v[34:35], v[6:7]
	v_mov_b64_e32 v[42:43], v[6:7]
	v_mov_b64_e32 v[50:51], v[6:7]
	v_mov_b64_e32 v[58:59], v[6:7]
	v_mov_b64_e32 v[66:67], v[6:7]
	s_mov_b32 s2, 0
	v_ashrrev_i32_e32 v125, 31, v124
	v_mov_b64_e32 v[12:13], v[4:5]
	v_mov_b64_e32 v[20:21], v[4:5]
	v_mov_b64_e32 v[28:29], v[4:5]
	v_mov_b64_e32 v[36:37], v[4:5]
	v_mov_b64_e32 v[44:45], v[4:5]
	v_mov_b64_e32 v[52:53], v[4:5]
	v_mov_b64_e32 v[60:61], v[4:5]
	v_mov_b64_e32 v[8:9], v[4:5]
	v_mov_b64_e32 v[16:17], v[4:5]
	v_mov_b64_e32 v[24:25], v[4:5]
	v_mov_b64_e32 v[32:33], v[4:5]
	v_mov_b64_e32 v[40:41], v[4:5]
	v_mov_b64_e32 v[48:49], v[4:5]
	v_mov_b64_e32 v[56:57], v[4:5]
	v_mov_b64_e32 v[64:65], v[4:5]
	s_waitcnt vmcnt(0)
